# MLA loop: second tile of each barrier interval issues its LDS store / reload pieces six MFMA slots earlier (slots 8-10)
# baseline (speedup 1.0000x reference)
; #define SB() __builtin_amdgcn_sched_barrier(0)
; template <int VAR>
; __device__ __forceinline__ void attn_phase(LAS unsigned char* lds, const AttnP P, int vcu, int G, int wave_s) {
;     ...
;                 if (ND0 == 6) {
;                     KR1(0); KR1(1); KR1(2); KR1(3); SB();
;                     QK1(0, negm); EX2(pc0, 0, w0.x); KR1(4); SB();
;                     QK1(1, negm); EX2(pc0, 2, w0.y); KR1(5); SB();
;                     QK1(2, pn0); EX2(pc0, 4, w0.z); KR1(6); SB();
;                     QK1(3, pn1); EX2(pc0, 6, w0.w); KR1(7); SB();
;                     QK1(4, pn0); EX2(pc0, 8, w1.x); KR1(8); SB();
;                     QK1(5, pn1); EX2(pc0, 10, w1.y); KR1(9); SB();
;                     QK1(6, pn0); EX2(pc0, 12, w1.z); KR1(10); SB();
;                     QK1(7, pn1); EX2(pc0, 14, w1.w); KR1(11); SB();
;                     QK1(8, pn0); EX2(pc1, 0, w2.x); VR1(0); SB();
;                     QK1(9, pn1); EX2(pc1, 2, w2.y); VR1(1); SB();
;                     QK1(10, pn0); EX2(pc1, 4, w2.z); VR1(2); SB();
;                     QK1(11, pn1); EX2(pc1, 6, w2.w); VR1(3); SB();
;                 } else {
;                     KR1(0); KR1(1); KR1(2); KR1(3); SB();
;                     QK1(0, negm); EX2(pc0, 0, w0.x); EX2(pc0, 2, w0.y); KR1(4); SB();
;                     QK1(1, negm); EX2(pc0, 4, w0.z); EX2(pc0, 6, w0.w); KR1(5); SB();
;                     QK1(2, pn0); EX2(pc0, 8, w1.x); EX2(pc0, 10, w1.y); KR1(6); SB();
;                     QK1(3, pn1); EX2(pc0, 12, w1.z); EX2(pc0, 14, w1.w); KR1(7); SB();
;                     QK1(4, pn0); EX2(pc1, 0, w2.x); VR1(0); SB();
;                     QK1(5, pn1); EX2(pc1, 2, w2.y); VR1(1); SB();
;                     QK1(6, pn0); EX2(pc1, 4, w2.z); VR1(2); SB();
;                     QK1(7, pn1); EX2(pc1, 6, w2.w); VR1(3); SB();
;                 }
;                 PV1(0, w0); EX2(pc1, 8, w3.x); VR1(4); SB();
;                 PV1(1, w0); EX2(pc1, 10, w3.y); VR1(5); SB();
;                 PV1(2, w1); EX2(pc1, 12, w3.z); VR1(6); SB();
;                 PV1(3, w1); EX2(pc1, 14, w3.w); VR1(7); SB();
;                 lrun += sacc;
;                 PV1(4, w2); MASK_TILE(pn0, pn1, t + 1); SB();
;                 PV1(5, w2); SB();
;                 PV1(6, w3); SB();
;                 PV1(7, w3); rmn = rowmax32(pn0, pn1); if (!USE_NEGM) rmn -= mref; SB();
.Lmla_p1_go:
	v_exp_f32_e32 v222, v82
	v_exp_f32_e32 v223, v83
	v_add_f32_e32 v164, 0, v222
	v_cvt_pk_bf16_f32 v206, v222, v223
	v_add_f32_e32 v164, v223, v164
	v_exp_f32_e32 v224, v84
	v_exp_f32_e32 v225, v85
	v_add_f32_e32 v164, v224, v164
	v_cvt_pk_bf16_f32 v207, v224, v225
	v_add_f32_e32 v164, v225, v164
	s_waitcnt lgkmcnt(4)
	v_mfma_f32_32x32x16_bf16 v[34:49], v[182:185], v[114:117], v[66:81]
	ds_read_b128 v[198:201], v174 offset:45120
	v_exp_f32_e32 v222, v86
	v_exp_f32_e32 v223, v87
	v_add_f32_e32 v164, v222, v164
	v_cvt_pk_bf16_f32 v208, v222, v223
	v_add_f32_e32 v164, v223, v164
	s_waitcnt lgkmcnt(4)
	v_mfma_f32_32x32x16_bf16 v[50:65], v[186:189], v[114:117], v[66:81]
	ds_read_b128 v[182:185], v174 offset:51776
	v_exp_f32_e32 v224, v88
	v_exp_f32_e32 v225, v89
	v_add_f32_e32 v164, v224, v164
	v_cvt_pk_bf16_f32 v209, v224, v225
	v_add_f32_e32 v164, v225, v164
	s_waitcnt lgkmcnt(3)
	v_mfma_f32_32x32x16_bf16 v[34:49], v[190:193], v[118:121], v[34:49]
	ds_read_b128 v[186:189], v174 offset:45152
	v_exp_f32_e32 v222, v90
	v_exp_f32_e32 v223, v91
	v_add_f32_e32 v164, v222, v164
	v_cvt_pk_bf16_f32 v210, v222, v223
	v_add_f32_e32 v164, v223, v164
	s_waitcnt lgkmcnt(3)
	v_mfma_f32_32x32x16_bf16 v[50:65], v[194:197], v[118:121], v[50:65]
	ds_read_b128 v[190:193], v174 offset:51808
	v_exp_f32_e32 v224, v92
	v_exp_f32_e32 v225, v93
	v_add_f32_e32 v164, v224, v164
	v_cvt_pk_bf16_f32 v211, v224, v225
	v_add_f32_e32 v164, v225, v164
	s_waitcnt lgkmcnt(3)
	v_mfma_f32_32x32x16_bf16 v[34:49], v[198:201], v[122:125], v[34:49]
	ds_read_b128 v[194:197], v174 offset:45184
	v_exp_f32_e32 v222, v94
	v_exp_f32_e32 v223, v95
	v_add_f32_e32 v164, v222, v164
	v_cvt_pk_bf16_f32 v212, v222, v223
	v_add_f32_e32 v164, v223, v164
	s_waitcnt lgkmcnt(3)
	v_mfma_f32_32x32x16_bf16 v[50:65], v[182:185], v[122:125], v[50:65]
	ds_read_b128 v[198:201], v174 offset:51840
	v_exp_f32_e32 v224, v96
	v_exp_f32_e32 v225, v97
	v_add_f32_e32 v164, v224, v164
	v_cvt_pk_bf16_f32 v213, v224, v225
	v_add_f32_e32 v164, v225, v164
	s_waitcnt lgkmcnt(3)
	v_mfma_f32_32x32x16_bf16 v[34:49], v[186:189], v[126:129], v[34:49]
	ds_read_b128 v[182:185], v174 offset:45216
	v_exp_f32_e32 v222, v98
	v_exp_f32_e32 v223, v99
	v_add_f32_e32 v164, v222, v164
	v_cvt_pk_bf16_f32 v214, v222, v223
	v_add_f32_e32 v164, v223, v164
	s_waitcnt lgkmcnt(3)
	v_mfma_f32_32x32x16_bf16 v[50:65], v[190:193], v[126:129], v[50:65]
	ds_read_b128 v[186:189], v174 offset:51872
	v_exp_f32_e32 v224, v100
	v_exp_f32_e32 v225, v101
	v_add_f32_e32 v164, v224, v164
	v_cvt_pk_bf16_f32 v215, v224, v225
	v_add_f32_e32 v164, v225, v164
	s_mov_b32 s13, s20
	s_mov_b32 s20, s19
	s_add_i32 s19, s19, 1
	s_cmp_eq_u32 s19, s9
	s_cselect_b32 s19, 0, s19
	s_waitcnt lgkmcnt(3)
	v_mfma_f32_32x32x16_bf16 v[34:49], v[194:197], v[130:133], v[34:49]
	ds_read_b128 v[190:193], v228 offset:35840
	v_exp_f32_e32 v222, v102
	v_exp_f32_e32 v223, v103
	v_add_f32_e32 v164, v222, v164
	v_cvt_pk_bf16_f32 v216, v222, v223
	v_add_f32_e32 v164, v223, v164
	s_waitcnt vmcnt(2)
	ds_write_b128 v172, v[150:153]
	v_lshl_add_u32 v222, s19, 17, v178
	global_load_dwordx4 v[150:153], v222, s[52:53]
	s_waitcnt lgkmcnt(4)
	v_mfma_f32_32x32x16_bf16 v[50:65], v[198:201], v[130:133], v[50:65]
	ds_read_b128 v[194:197], v228 offset:40448
	v_exp_f32_e32 v224, v104
	v_exp_f32_e32 v225, v105
	v_add_f32_e32 v164, v224, v164
	v_cvt_pk_bf16_f32 v217, v224, v225
	v_add_f32_e32 v164, v225, v164
	s_and_b64 vcc, exec, s[2:3]
	s_cbranch_vccz .Lmla_p1_nope
	ds_write_b128 v176, v[160:163] offset:128
	v_lshl_add_u32 v222, s19, 12, v179
	global_load_dwordx4 v[160:163], v222, s[62:63]
.Lmla_p1_nope:
	s_waitcnt lgkmcnt(4)
	v_mfma_f32_32x32x16_bf16 v[34:49], v[182:185], v[134:137], v[34:49]
	ds_read_b128 v[198:201], v228 offset:35872
	v_exp_f32_e32 v222, v106
	v_exp_f32_e32 v223, v107
	v_add_f32_e32 v164, v222, v164
	v_cvt_pk_bf16_f32 v218, v222, v223
	v_add_f32_e32 v164, v223, v164
	v_add_u32_e32 v222, 0xb000, v173
	ds_write_b128 v222, v[202:205] offset:49152
	v_lshl_add_u32 v222, s13, 7, v168
	global_load_dwordx4 v[202:205], v222, s[56:57]
	s_waitcnt lgkmcnt(5)
	v_mfma_f32_32x32x16_bf16 v[50:65], v[186:189], v[134:137], v[50:65]
	ds_read_b128 v[182:185], v228 offset:40480
	v_exp_f32_e32 v224, v108
	v_exp_f32_e32 v225, v109
	v_add_f32_e32 v164, v224, v164
	v_cvt_pk_bf16_f32 v219, v224, v225
	v_add_f32_e32 v164, v225, v164
	s_waitcnt lgkmcnt(5)
	v_mfma_f32_32x32x16_bf16 v[2:17], v[190:193], v[206:209], v[2:17]
	ds_read_b128 v[186:189], v228 offset:35904
	v_exp_f32_e32 v222, v110
	v_exp_f32_e32 v223, v111
	v_add_f32_e32 v164, v222, v164
	v_cvt_pk_bf16_f32 v220, v222, v223
	v_add_f32_e32 v164, v223, v164
	s_waitcnt lgkmcnt(4)
	v_mfma_f32_32x32x16_bf16 v[18:33], v[194:197], v[206:209], v[18:33]
	ds_read_b128 v[190:193], v228 offset:40512
	v_exp_f32_e32 v224, v112
	v_exp_f32_e32 v225, v113
	v_add_f32_e32 v164, v224, v164
	v_cvt_pk_bf16_f32 v221, v224, v225
	v_add_f32_e32 v164, v225, v164
	s_waitcnt lgkmcnt(4)
	v_mfma_f32_32x32x16_bf16 v[2:17], v[198:201], v[210:213], v[2:17]
	ds_read_b128 v[194:197], v228 offset:35936
	v_max3_f32 v224, v34, v35, v36
	v_max3_f32 v225, v50, v51, v52
	v_max3_f32 v224, v224, v37, v38
	v_max3_f32 v225, v225, v53, v54
	s_waitcnt lgkmcnt(3)
	v_mfma_f32_32x32x16_bf16 v[18:33], v[182:185], v[210:213], v[18:33]
	ds_read_b128 v[198:201], v228 offset:40544
	ds_read_b128 v[182:185], v229 offset:13312
	v_max3_f32 v224, v224, v39, v40
	v_max3_f32 v225, v225, v55, v56
	v_max3_f32 v224, v224, v41, v42
	v_max3_f32 v225, v225, v57, v58
	s_waitcnt lgkmcnt(4)
	v_mfma_f32_32x32x16_bf16 v[2:17], v[186:189], v[214:217], v[2:17]
	ds_read_b128 v[186:189], v229 offset:19968
	v_max3_f32 v224, v224, v43, v44
	v_max3_f32 v225, v225, v59, v60
	v_max3_f32 v224, v224, v45, v46
	v_max3_f32 v225, v225, v61, v62
	s_waitcnt lgkmcnt(4)
	v_mfma_f32_32x32x16_bf16 v[18:33], v[190:193], v[214:217], v[18:33]
	ds_read_b128 v[190:193], v229 offset:13344
	v_max3_f32 v224, v224, v47, v48
	v_max3_f32 v225, v225, v63, v64
	v_max3_f32 v224, v224, v49, v65
	v_max_f32_e32 v224, v224, v225
	s_waitcnt lgkmcnt(4)
	v_mfma_f32_32x32x16_bf16 v[2:17], v[194:197], v[218:221], v[2:17]
	ds_read_b128 v[194:197], v229 offset:20000
	v_mov_b32_e32 v225, v224
	v_add_f32_e32 v1, v1, v164
	s_add_i32 s11, s11, 1
	v_permlane32_swap_b32_e32 v224, v225
	s_cmp_eq_u32 s9, s11
	v_max_f32_e32 v167, v224, v225
	v_cmp_lt_f32_e32 vcc, s66, v167
	s_waitcnt lgkmcnt(4)
	v_mfma_f32_32x32x16_bf16 v[18:33], v[198:201], v[218:221], v[18:33]
	s_waitcnt lgkmcnt(9)
	s_barrier

; #define SB() __builtin_amdgcn_sched_barrier(0)
; template <int VAR>
; __device__ __forceinline__ void attn_phase(LAS unsigned char* lds, const AttnP P, int vcu, int G, int wave_s) {
;     ...
;                 if (ND0 == 6) {
;                     KR1(0); KR1(1); KR1(2); KR1(3); SB();
;                     QK1(0, negm); EX2(pc0, 0, w0.x); KR1(4); SB();
;                     QK1(1, negm); EX2(pc0, 2, w0.y); KR1(5); SB();
;                     QK1(2, pn0); EX2(pc0, 4, w0.z); KR1(6); SB();
;                     QK1(3, pn1); EX2(pc0, 6, w0.w); KR1(7); SB();
;                     QK1(4, pn0); EX2(pc0, 8, w1.x); KR1(8); SB();
;                     QK1(5, pn1); EX2(pc0, 10, w1.y); KR1(9); SB();
;                     QK1(6, pn0); EX2(pc0, 12, w1.z); KR1(10); SB();
;                     QK1(7, pn1); EX2(pc0, 14, w1.w); KR1(11); SB();
;                     QK1(8, pn0); EX2(pc1, 0, w2.x); VR1(0); SB();
;                     QK1(9, pn1); EX2(pc1, 2, w2.y); VR1(1); SB();
;                     QK1(10, pn0); EX2(pc1, 4, w2.z); VR1(2); SB();
;                     QK1(11, pn1); EX2(pc1, 6, w2.w); VR1(3); SB();
;                 } else {
;                     KR1(0); KR1(1); KR1(2); KR1(3); SB();
;                     QK1(0, negm); EX2(pc0, 0, w0.x); EX2(pc0, 2, w0.y); KR1(4); SB();
;                     QK1(1, negm); EX2(pc0, 4, w0.z); EX2(pc0, 6, w0.w); KR1(5); SB();
;                     QK1(2, pn0); EX2(pc0, 8, w1.x); EX2(pc0, 10, w1.y); KR1(6); SB();
;                     QK1(3, pn1); EX2(pc0, 12, w1.z); EX2(pc0, 14, w1.w); KR1(7); SB();
;                     QK1(4, pn0); EX2(pc1, 0, w2.x); VR1(0); SB();
;                     QK1(5, pn1); EX2(pc1, 2, w2.y); VR1(1); SB();
;                     QK1(6, pn0); EX2(pc1, 4, w2.z); VR1(2); SB();
;                     QK1(7, pn1); EX2(pc1, 6, w2.w); VR1(3); SB();
;                 }
;                 PV1(0, w0); EX2(pc1, 8, w3.x); VR1(4); SB();
;                 PV1(1, w0); EX2(pc1, 10, w3.y); VR1(5); SB();
;                 PV1(2, w1); EX2(pc1, 12, w3.z); VR1(6); SB();
;                 PV1(3, w1); EX2(pc1, 14, w3.w); VR1(7); SB();
;                 lrun += sacc;
;                 PV1(4, w2); MASK_TILE(pn0, pn1, t + 1); SB();
;                 PV1(5, w2); SB();
;                 PV1(6, w3); SB();
;                 PV1(7, w3); rmn = rowmax32(pn0, pn1); if (!USE_NEGM) rmn -= mref; SB();
.Lmla_p3_go:
	v_exp_f32_e32 v222, v82
	v_exp_f32_e32 v223, v83
	v_add_f32_e32 v164, 0, v222
	v_cvt_pk_bf16_f32 v206, v222, v223
	v_add_f32_e32 v164, v223, v164
	v_exp_f32_e32 v224, v84
	v_exp_f32_e32 v225, v85
	v_add_f32_e32 v164, v224, v164
	v_cvt_pk_bf16_f32 v207, v224, v225
	v_add_f32_e32 v164, v225, v164
	s_waitcnt lgkmcnt(4)
	v_mfma_f32_32x32x16_bf16 v[34:49], v[182:185], v[114:117], v[66:81]
	ds_read_b128 v[198:201], v229 offset:26688
	v_exp_f32_e32 v222, v86
	v_exp_f32_e32 v223, v87
	v_add_f32_e32 v164, v222, v164
	v_cvt_pk_bf16_f32 v208, v222, v223
	v_add_f32_e32 v164, v223, v164
	s_waitcnt lgkmcnt(4)
	v_mfma_f32_32x32x16_bf16 v[50:65], v[186:189], v[114:117], v[66:81]
	ds_read_b128 v[182:185], v229 offset:33344
	v_exp_f32_e32 v224, v88
	v_exp_f32_e32 v225, v89
	v_add_f32_e32 v164, v224, v164
	v_cvt_pk_bf16_f32 v209, v224, v225
	v_add_f32_e32 v164, v225, v164
	s_waitcnt lgkmcnt(3)
	v_mfma_f32_32x32x16_bf16 v[34:49], v[190:193], v[118:121], v[34:49]
	ds_read_b128 v[186:189], v229 offset:26720
	v_exp_f32_e32 v222, v90
	v_exp_f32_e32 v223, v91
	v_add_f32_e32 v164, v222, v164
	v_cvt_pk_bf16_f32 v210, v222, v223
	v_add_f32_e32 v164, v223, v164
	s_waitcnt lgkmcnt(3)
	v_mfma_f32_32x32x16_bf16 v[50:65], v[194:197], v[118:121], v[50:65]
	ds_read_b128 v[190:193], v229 offset:33376
	v_exp_f32_e32 v224, v92
	v_exp_f32_e32 v225, v93
	v_add_f32_e32 v164, v224, v164
	v_cvt_pk_bf16_f32 v211, v224, v225
	v_add_f32_e32 v164, v225, v164
	s_waitcnt lgkmcnt(3)
	v_mfma_f32_32x32x16_bf16 v[34:49], v[198:201], v[122:125], v[34:49]
	ds_read_b128 v[194:197], v229 offset:26752
	v_exp_f32_e32 v222, v94
	v_exp_f32_e32 v223, v95
	v_add_f32_e32 v164, v222, v164
	v_cvt_pk_bf16_f32 v212, v222, v223
	v_add_f32_e32 v164, v223, v164
	s_waitcnt lgkmcnt(3)
	v_mfma_f32_32x32x16_bf16 v[50:65], v[182:185], v[122:125], v[50:65]
	ds_read_b128 v[198:201], v229 offset:33408
	v_exp_f32_e32 v224, v96
	v_exp_f32_e32 v225, v97
	v_add_f32_e32 v164, v224, v164
	v_cvt_pk_bf16_f32 v213, v224, v225
	v_add_f32_e32 v164, v225, v164
	s_waitcnt lgkmcnt(3)
	v_mfma_f32_32x32x16_bf16 v[34:49], v[186:189], v[126:129], v[34:49]
	ds_read_b128 v[182:185], v229 offset:26784
	v_exp_f32_e32 v222, v98
	v_exp_f32_e32 v223, v99
	v_add_f32_e32 v164, v222, v164
	v_cvt_pk_bf16_f32 v214, v222, v223
	v_add_f32_e32 v164, v223, v164
	s_waitcnt lgkmcnt(3)
	v_mfma_f32_32x32x16_bf16 v[50:65], v[190:193], v[126:129], v[50:65]
	ds_read_b128 v[186:189], v229 offset:33440
	v_exp_f32_e32 v224, v100
	v_exp_f32_e32 v225, v101
	v_add_f32_e32 v164, v224, v164
	v_cvt_pk_bf16_f32 v215, v224, v225
	v_add_f32_e32 v164, v225, v164
	s_mov_b32 s13, s20
	s_mov_b32 s20, s19
	s_add_i32 s19, s19, 1
	s_cmp_eq_u32 s19, s9
	s_cselect_b32 s19, 0, s19
	s_waitcnt lgkmcnt(3)
	v_mfma_f32_32x32x16_bf16 v[34:49], v[194:197], v[130:133], v[34:49]
	ds_read_b128 v[190:193], v181 offset:49152
	v_exp_f32_e32 v222, v102
	v_exp_f32_e32 v223, v103
	v_add_f32_e32 v164, v222, v164
	v_cvt_pk_bf16_f32 v216, v222, v223
	v_add_f32_e32 v164, v223, v164
	s_waitcnt vmcnt(2)
	ds_write_b128 v172, v[150:153] offset:45056
	v_lshl_add_u32 v222, s19, 17, v178
	global_load_dwordx4 v[150:153], v222, s[52:53]
	s_waitcnt lgkmcnt(4)
	v_mfma_f32_32x32x16_bf16 v[50:65], v[198:201], v[130:133], v[50:65]
	ds_read_b128 v[194:197], v181 offset:53760
	v_exp_f32_e32 v224, v104
	v_exp_f32_e32 v225, v105
	v_add_f32_e32 v164, v224, v164
	v_cvt_pk_bf16_f32 v217, v224, v225
	v_add_f32_e32 v164, v225, v164
	s_and_b64 vcc, exec, s[2:3]
	s_cbranch_vccz .Lmla_p3_nope
	ds_write_b128 v176, v[160:163] offset:45184
	v_lshl_add_u32 v222, s19, 12, v179
	global_load_dwordx4 v[160:163], v222, s[62:63]
.Lmla_p3_nope:
	s_waitcnt lgkmcnt(4)
	v_mfma_f32_32x32x16_bf16 v[34:49], v[182:185], v[134:137], v[34:49]
	ds_read_b128 v[198:201], v181 offset:49184
	v_exp_f32_e32 v222, v106
	v_exp_f32_e32 v223, v107
	v_add_f32_e32 v164, v222, v164
	v_cvt_pk_bf16_f32 v218, v222, v223
	v_add_f32_e32 v164, v223, v164
	ds_write_b128 v173, v[202:205] offset:35840
	v_lshl_add_u32 v222, s13, 7, v168
	global_load_dwordx4 v[202:205], v222, s[56:57]
	s_waitcnt lgkmcnt(5)
	v_mfma_f32_32x32x16_bf16 v[50:65], v[186:189], v[134:137], v[50:65]
	ds_read_b128 v[182:185], v181 offset:53792
	v_exp_f32_e32 v224, v108
	v_exp_f32_e32 v225, v109
	v_add_f32_e32 v164, v224, v164
	v_cvt_pk_bf16_f32 v219, v224, v225
	v_add_f32_e32 v164, v225, v164
	s_waitcnt lgkmcnt(5)
	v_mfma_f32_32x32x16_bf16 v[2:17], v[190:193], v[206:209], v[2:17]
	ds_read_b128 v[186:189], v181 offset:49216
	v_exp_f32_e32 v222, v110
	v_exp_f32_e32 v223, v111
	v_add_f32_e32 v164, v222, v164
	v_cvt_pk_bf16_f32 v220, v222, v223
	v_add_f32_e32 v164, v223, v164
	s_waitcnt lgkmcnt(4)
	v_mfma_f32_32x32x16_bf16 v[18:33], v[194:197], v[206:209], v[18:33]
	ds_read_b128 v[190:193], v181 offset:53824
	v_exp_f32_e32 v224, v112
	v_exp_f32_e32 v225, v113
	v_add_f32_e32 v164, v224, v164
	v_cvt_pk_bf16_f32 v221, v224, v225
	v_add_f32_e32 v164, v225, v164
	s_waitcnt lgkmcnt(4)
	v_mfma_f32_32x32x16_bf16 v[2:17], v[198:201], v[210:213], v[2:17]
	ds_read_b128 v[194:197], v181 offset:49248
	v_max3_f32 v224, v34, v35, v36
	v_max3_f32 v225, v50, v51, v52
	v_max3_f32 v224, v224, v37, v38
	v_max3_f32 v225, v225, v53, v54
	s_waitcnt lgkmcnt(3)
	v_mfma_f32_32x32x16_bf16 v[18:33], v[182:185], v[210:213], v[18:33]
	ds_read_b128 v[198:201], v181 offset:53856
	ds_read_b128 v[182:185], v174
	v_max3_f32 v224, v224, v39, v40
	v_max3_f32 v225, v225, v55, v56
	v_max3_f32 v224, v224, v41, v42
	v_max3_f32 v225, v225, v57, v58
	s_waitcnt lgkmcnt(4)
	v_mfma_f32_32x32x16_bf16 v[2:17], v[186:189], v[214:217], v[2:17]
	ds_read_b128 v[186:189], v174 offset:6656
	v_max3_f32 v224, v224, v43, v44
	v_max3_f32 v225, v225, v59, v60
	v_max3_f32 v224, v224, v45, v46
	v_max3_f32 v225, v225, v61, v62
	s_waitcnt lgkmcnt(4)
	v_mfma_f32_32x32x16_bf16 v[18:33], v[190:193], v[214:217], v[18:33]
	ds_read_b128 v[190:193], v174 offset:32
	v_max3_f32 v224, v224, v47, v48
	v_max3_f32 v225, v225, v63, v64
	v_max3_f32 v224, v224, v49, v65
	v_max_f32_e32 v224, v224, v225
	s_waitcnt lgkmcnt(4)
	v_mfma_f32_32x32x16_bf16 v[2:17], v[194:197], v[218:221], v[2:17]
	ds_read_b128 v[194:197], v174 offset:6688
	v_mov_b32_e32 v225, v224
	v_add_f32_e32 v1, v1, v164
	s_add_i32 s11, s11, 1
	v_permlane32_swap_b32_e32 v224, v225
	s_cmp_eq_u32 s9, s11
	v_max_f32_e32 v167, v224, v225
	v_cmp_lt_f32_e32 vcc, s66, v167
	s_waitcnt lgkmcnt(4)
	v_mfma_f32_32x32x16_bf16 v[18:33], v[198:201], v[218:221], v[18:33]
	s_waitcnt lgkmcnt(9)
	s_barrier

; #define SB() __builtin_amdgcn_sched_barrier(0)
; template <int VAR>
; __device__ __forceinline__ void attn_phase(LAS unsigned char* lds, const AttnP P, int vcu, int G, int wave_s) {
;     ...
;                 if (ND0 == 6) {
;                     KR1(0); KR1(1); KR1(2); KR1(3); SB();
;                     QK1(0, negm); EX2(pc0, 0, w0.x); KR1(4); SB();
;                     QK1(1, negm); EX2(pc0, 2, w0.y); KR1(5); SB();
;                     QK1(2, pn0); EX2(pc0, 4, w0.z); KR1(6); SB();
;                     QK1(3, pn1); EX2(pc0, 6, w0.w); KR1(7); SB();
;                     QK1(4, pn0); EX2(pc0, 8, w1.x); KR1(8); SB();
;                     QK1(5, pn1); EX2(pc0, 10, w1.y); KR1(9); SB();
;                     QK1(6, pn0); EX2(pc0, 12, w1.z); KR1(10); SB();
;                     QK1(7, pn1); EX2(pc0, 14, w1.w); KR1(11); SB();
;                     QK1(8, pn0); EX2(pc1, 0, w2.x); VR1(0); SB();
;                     QK1(9, pn1); EX2(pc1, 2, w2.y); VR1(1); SB();
;                     QK1(10, pn0); EX2(pc1, 4, w2.z); VR1(2); SB();
;                     QK1(11, pn1); EX2(pc1, 6, w2.w); VR1(3); SB();
;                 } else {
;                     KR1(0); KR1(1); KR1(2); KR1(3); SB();
;                     QK1(0, negm); EX2(pc0, 0, w0.x); EX2(pc0, 2, w0.y); KR1(4); SB();
;                     QK1(1, negm); EX2(pc0, 4, w0.z); EX2(pc0, 6, w0.w); KR1(5); SB();
;                     QK1(2, pn0); EX2(pc0, 8, w1.x); EX2(pc0, 10, w1.y); KR1(6); SB();
;                     QK1(3, pn1); EX2(pc0, 12, w1.z); EX2(pc0, 14, w1.w); KR1(7); SB();
;                     QK1(4, pn0); EX2(pc1, 0, w2.x); VR1(0); SB();
;                     QK1(5, pn1); EX2(pc1, 2, w2.y); VR1(1); SB();
;                     QK1(6, pn0); EX2(pc1, 4, w2.z); VR1(2); SB();
;                     QK1(7, pn1); EX2(pc1, 6, w2.w); VR1(3); SB();
;                 }
;                 PV1(0, w0); EX2(pc1, 8, w3.x); VR1(4); SB();
;                 PV1(1, w0); EX2(pc1, 10, w3.y); VR1(5); SB();
;                 PV1(2, w1); EX2(pc1, 12, w3.z); VR1(6); SB();
;                 PV1(3, w1); EX2(pc1, 14, w3.w); VR1(7); SB();
;                 lrun += sacc;
;                 PV1(4, w2); MASK_TILE(pn0, pn1, t + 1); SB();
;                 PV1(5, w2); SB();
;                 PV1(6, w3); SB();
;                 PV1(7, w3); rmn = rowmax32(pn0, pn1); if (!USE_NEGM) rmn -= mref; SB();
.Lmla_p5_go:
	v_exp_f32_e32 v222, v82
	v_exp_f32_e32 v223, v83
	v_add_f32_e32 v164, 0, v222
	v_cvt_pk_bf16_f32 v206, v222, v223
	v_add_f32_e32 v164, v223, v164
	v_exp_f32_e32 v224, v84
	v_exp_f32_e32 v225, v85
	v_add_f32_e32 v164, v224, v164
	v_cvt_pk_bf16_f32 v207, v224, v225
	v_add_f32_e32 v164, v225, v164
	s_waitcnt lgkmcnt(4)
	v_mfma_f32_32x32x16_bf16 v[34:49], v[182:185], v[114:117], v[66:81]
	ds_read_b128 v[198:201], v174 offset:22592
	v_exp_f32_e32 v222, v86
	v_exp_f32_e32 v223, v87
	v_add_f32_e32 v164, v222, v164
	v_cvt_pk_bf16_f32 v208, v222, v223
	v_add_f32_e32 v164, v223, v164
	s_waitcnt lgkmcnt(4)
	v_mfma_f32_32x32x16_bf16 v[50:65], v[186:189], v[114:117], v[66:81]
	ds_read_b128 v[182:185], v174 offset:29248
	v_exp_f32_e32 v224, v88
	v_exp_f32_e32 v225, v89
	v_add_f32_e32 v164, v224, v164
	v_cvt_pk_bf16_f32 v209, v224, v225
	v_add_f32_e32 v164, v225, v164
	s_waitcnt lgkmcnt(3)
	v_mfma_f32_32x32x16_bf16 v[34:49], v[190:193], v[118:121], v[34:49]
	ds_read_b128 v[186:189], v174 offset:22624
	v_exp_f32_e32 v222, v90
	v_exp_f32_e32 v223, v91
	v_add_f32_e32 v164, v222, v164
	v_cvt_pk_bf16_f32 v210, v222, v223
	v_add_f32_e32 v164, v223, v164
	s_waitcnt lgkmcnt(3)
	v_mfma_f32_32x32x16_bf16 v[50:65], v[194:197], v[118:121], v[50:65]
	ds_read_b128 v[190:193], v174 offset:29280
	v_exp_f32_e32 v224, v92
	v_exp_f32_e32 v225, v93
	v_add_f32_e32 v164, v224, v164
	v_cvt_pk_bf16_f32 v211, v224, v225
	v_add_f32_e32 v164, v225, v164
	s_waitcnt lgkmcnt(3)
	v_mfma_f32_32x32x16_bf16 v[34:49], v[198:201], v[122:125], v[34:49]
	ds_read_b128 v[194:197], v174 offset:22656
	v_exp_f32_e32 v222, v94
	v_exp_f32_e32 v223, v95
	v_add_f32_e32 v164, v222, v164
	v_cvt_pk_bf16_f32 v212, v222, v223
	v_add_f32_e32 v164, v223, v164
	s_waitcnt lgkmcnt(3)
	v_mfma_f32_32x32x16_bf16 v[50:65], v[182:185], v[122:125], v[50:65]
	ds_read_b128 v[198:201], v174 offset:29312
	v_exp_f32_e32 v224, v96
	v_exp_f32_e32 v225, v97
	v_add_f32_e32 v164, v224, v164
	v_cvt_pk_bf16_f32 v213, v224, v225
	v_add_f32_e32 v164, v225, v164
	s_waitcnt lgkmcnt(3)
	v_mfma_f32_32x32x16_bf16 v[34:49], v[186:189], v[126:129], v[34:49]
	ds_read_b128 v[182:185], v174 offset:22688
	v_exp_f32_e32 v222, v98
	v_exp_f32_e32 v223, v99
	v_add_f32_e32 v164, v222, v164
	v_cvt_pk_bf16_f32 v214, v222, v223
	v_add_f32_e32 v164, v223, v164
	s_waitcnt lgkmcnt(3)
	v_mfma_f32_32x32x16_bf16 v[50:65], v[190:193], v[126:129], v[50:65]
	ds_read_b128 v[186:189], v174 offset:29344
	v_exp_f32_e32 v224, v100
	v_exp_f32_e32 v225, v101
	v_add_f32_e32 v164, v224, v164
	v_cvt_pk_bf16_f32 v215, v224, v225
	v_add_f32_e32 v164, v225, v164
	s_mov_b32 s13, s20
	s_mov_b32 s20, s19
	s_add_i32 s19, s19, 1
	s_cmp_eq_u32 s19, s9
	s_cselect_b32 s19, 0, s19
	s_waitcnt lgkmcnt(3)
	v_mfma_f32_32x32x16_bf16 v[34:49], v[194:197], v[130:133], v[34:49]
	ds_read_b128 v[190:193], v228 offset:35840
	v_exp_f32_e32 v222, v102
	v_exp_f32_e32 v223, v103
	v_add_f32_e32 v164, v222, v164
	v_cvt_pk_bf16_f32 v216, v222, v223
	v_add_f32_e32 v164, v223, v164
	s_waitcnt vmcnt(2)
	v_add_u32_e32 v222, 0xb000, v172
	ds_write_b128 v222, v[150:153] offset:26624
	v_lshl_add_u32 v222, s19, 17, v178
	global_load_dwordx4 v[150:153], v222, s[52:53]
	s_waitcnt lgkmcnt(4)
	v_mfma_f32_32x32x16_bf16 v[50:65], v[198:201], v[130:133], v[50:65]
	ds_read_b128 v[194:197], v228 offset:40448
	v_exp_f32_e32 v224, v104
	v_exp_f32_e32 v225, v105
	v_add_f32_e32 v164, v224, v164
	v_cvt_pk_bf16_f32 v217, v224, v225
	v_add_f32_e32 v164, v225, v164
	s_and_b64 vcc, exec, s[2:3]
	s_cbranch_vccz .Lmla_p5_nope
	v_add_u32_e32 v222, 0xb000, v176
	ds_write_b128 v222, v[160:163] offset:26752
	v_lshl_add_u32 v222, s19, 12, v179
	global_load_dwordx4 v[160:163], v222, s[62:63]
.Lmla_p5_nope:
	s_waitcnt lgkmcnt(4)
	v_mfma_f32_32x32x16_bf16 v[34:49], v[182:185], v[134:137], v[34:49]
	ds_read_b128 v[198:201], v228 offset:35872
	v_exp_f32_e32 v222, v106
	v_exp_f32_e32 v223, v107
	v_add_f32_e32 v164, v222, v164
	v_cvt_pk_bf16_f32 v218, v222, v223
	v_add_f32_e32 v164, v223, v164
	v_add_u32_e32 v222, 0xb000, v173
	ds_write_b128 v222, v[202:205] offset:49152
	v_lshl_add_u32 v222, s13, 7, v168
	global_load_dwordx4 v[202:205], v222, s[56:57]
	s_waitcnt lgkmcnt(5)
	v_mfma_f32_32x32x16_bf16 v[50:65], v[186:189], v[134:137], v[50:65]
	ds_read_b128 v[182:185], v228 offset:40480
	v_exp_f32_e32 v224, v108
	v_exp_f32_e32 v225, v109
	v_add_f32_e32 v164, v224, v164
	v_cvt_pk_bf16_f32 v219, v224, v225
	v_add_f32_e32 v164, v225, v164
	s_waitcnt lgkmcnt(5)
	v_mfma_f32_32x32x16_bf16 v[2:17], v[190:193], v[206:209], v[2:17]
	ds_read_b128 v[186:189], v228 offset:35904
	v_exp_f32_e32 v222, v110
	v_exp_f32_e32 v223, v111
	v_add_f32_e32 v164, v222, v164
	v_cvt_pk_bf16_f32 v220, v222, v223
	v_add_f32_e32 v164, v223, v164
	s_waitcnt lgkmcnt(4)
	v_mfma_f32_32x32x16_bf16 v[18:33], v[194:197], v[206:209], v[18:33]
	ds_read_b128 v[190:193], v228 offset:40512
	v_exp_f32_e32 v224, v112
	v_exp_f32_e32 v225, v113
	v_add_f32_e32 v164, v224, v164
	v_cvt_pk_bf16_f32 v221, v224, v225
	v_add_f32_e32 v164, v225, v164
	s_waitcnt lgkmcnt(4)
	v_mfma_f32_32x32x16_bf16 v[2:17], v[198:201], v[210:213], v[2:17]
	ds_read_b128 v[194:197], v228 offset:35936
	v_max3_f32 v224, v34, v35, v36
	v_max3_f32 v225, v50, v51, v52
	v_max3_f32 v224, v224, v37, v38
	v_max3_f32 v225, v225, v53, v54
	s_waitcnt lgkmcnt(3)
	v_mfma_f32_32x32x16_bf16 v[18:33], v[182:185], v[210:213], v[18:33]
	ds_read_b128 v[198:201], v228 offset:40544
	ds_read_b128 v[182:185], v174 offset:45056
	v_max3_f32 v224, v224, v39, v40
	v_max3_f32 v225, v225, v55, v56
	v_max3_f32 v224, v224, v41, v42
	v_max3_f32 v225, v225, v57, v58
	s_waitcnt lgkmcnt(4)
	v_mfma_f32_32x32x16_bf16 v[2:17], v[186:189], v[214:217], v[2:17]
	ds_read_b128 v[186:189], v174 offset:51712
	v_max3_f32 v224, v224, v43, v44
	v_max3_f32 v225, v225, v59, v60
	v_max3_f32 v224, v224, v45, v46
	v_max3_f32 v225, v225, v61, v62
	s_waitcnt lgkmcnt(4)
	v_mfma_f32_32x32x16_bf16 v[18:33], v[190:193], v[214:217], v[18:33]
	ds_read_b128 v[190:193], v174 offset:45088
	v_max3_f32 v224, v224, v47, v48
	v_max3_f32 v225, v225, v63, v64
	v_max3_f32 v224, v224, v49, v65
	v_max_f32_e32 v224, v224, v225
	s_waitcnt lgkmcnt(4)
	v_mfma_f32_32x32x16_bf16 v[2:17], v[194:197], v[218:221], v[2:17]
	ds_read_b128 v[194:197], v174 offset:51744
	v_mov_b32_e32 v225, v224
	v_add_f32_e32 v1, v1, v164
	s_add_i32 s11, s11, 1
	v_permlane32_swap_b32_e32 v224, v225
	s_cmp_eq_u32 s9, s11
	v_max_f32_e32 v167, v224, v225
	v_cmp_lt_f32_e32 vcc, s66, v167
	s_waitcnt lgkmcnt(4)
	v_mfma_f32_32x32x16_bf16 v[18:33], v[198:201], v[218:221], v[18:33]
	s_waitcnt lgkmcnt(9)
	s_barrier

; #define SB() __builtin_amdgcn_sched_barrier(0)
; template <int VAR>
; __device__ __forceinline__ void attn_phase(LAS unsigned char* lds, const AttnP P, int vcu, int G, int wave_s) {
;     ...
;                 if (ND0 == 6) {
;                     KR1(0); KR1(1); KR1(2); KR1(3); SB();
;                     QK1(0, negm); EX2(pc0, 0, w0.x); KR1(4); SB();
;                     QK1(1, negm); EX2(pc0, 2, w0.y); KR1(5); SB();
;                     QK1(2, pn0); EX2(pc0, 4, w0.z); KR1(6); SB();
;                     QK1(3, pn1); EX2(pc0, 6, w0.w); KR1(7); SB();
;                     QK1(4, pn0); EX2(pc0, 8, w1.x); KR1(8); SB();
;                     QK1(5, pn1); EX2(pc0, 10, w1.y); KR1(9); SB();
;                     QK1(6, pn0); EX2(pc0, 12, w1.z); KR1(10); SB();
;                     QK1(7, pn1); EX2(pc0, 14, w1.w); KR1(11); SB();
;                     QK1(8, pn0); EX2(pc1, 0, w2.x); VR1(0); SB();
;                     QK1(9, pn1); EX2(pc1, 2, w2.y); VR1(1); SB();
;                     QK1(10, pn0); EX2(pc1, 4, w2.z); VR1(2); SB();
;                     QK1(11, pn1); EX2(pc1, 6, w2.w); VR1(3); SB();
;                 } else {
;                     KR1(0); KR1(1); KR1(2); KR1(3); SB();
;                     QK1(0, negm); EX2(pc0, 0, w0.x); EX2(pc0, 2, w0.y); KR1(4); SB();
;                     QK1(1, negm); EX2(pc0, 4, w0.z); EX2(pc0, 6, w0.w); KR1(5); SB();
;                     QK1(2, pn0); EX2(pc0, 8, w1.x); EX2(pc0, 10, w1.y); KR1(6); SB();
;                     QK1(3, pn1); EX2(pc0, 12, w1.z); EX2(pc0, 14, w1.w); KR1(7); SB();
;                     QK1(4, pn0); EX2(pc1, 0, w2.x); VR1(0); SB();
;                     QK1(5, pn1); EX2(pc1, 2, w2.y); VR1(1); SB();
;                     QK1(6, pn0); EX2(pc1, 4, w2.z); VR1(2); SB();
;                     QK1(7, pn1); EX2(pc1, 6, w2.w); VR1(3); SB();
;                 }
;                 PV1(0, w0); EX2(pc1, 8, w3.x); VR1(4); SB();
;                 PV1(1, w0); EX2(pc1, 10, w3.y); VR1(5); SB();
;                 PV1(2, w1); EX2(pc1, 12, w3.z); VR1(6); SB();
;                 PV1(3, w1); EX2(pc1, 14, w3.w); VR1(7); SB();
;                 lrun += sacc;
;                 PV1(4, w2); MASK_TILE(pn0, pn1, t + 1); SB();
;                 PV1(5, w2); SB();
;                 PV1(6, w3); SB();
;                 PV1(7, w3); rmn = rowmax32(pn0, pn1); if (!USE_NEGM) rmn -= mref; SB();
.Lmla_p7_go:
	v_exp_f32_e32 v222, v82
	v_exp_f32_e32 v223, v83
	v_add_f32_e32 v164, 0, v222
	v_cvt_pk_bf16_f32 v206, v222, v223
	v_add_f32_e32 v164, v223, v164
	v_exp_f32_e32 v224, v84
	v_exp_f32_e32 v225, v85
	v_add_f32_e32 v164, v224, v164
	v_cvt_pk_bf16_f32 v207, v224, v225
	v_add_f32_e32 v164, v225, v164
	s_waitcnt lgkmcnt(4)
	v_mfma_f32_32x32x16_bf16 v[34:49], v[182:185], v[114:117], v[66:81]
	ds_read_b128 v[198:201], v229 offset:13376
	v_exp_f32_e32 v222, v86
	v_exp_f32_e32 v223, v87
	v_add_f32_e32 v164, v222, v164
	v_cvt_pk_bf16_f32 v208, v222, v223
	v_add_f32_e32 v164, v223, v164
	s_waitcnt lgkmcnt(4)
	v_mfma_f32_32x32x16_bf16 v[50:65], v[186:189], v[114:117], v[66:81]
	ds_read_b128 v[182:185], v229 offset:20032
	v_exp_f32_e32 v224, v88
	v_exp_f32_e32 v225, v89
	v_add_f32_e32 v164, v224, v164
	v_cvt_pk_bf16_f32 v209, v224, v225
	v_add_f32_e32 v164, v225, v164
	s_waitcnt lgkmcnt(3)
	v_mfma_f32_32x32x16_bf16 v[34:49], v[190:193], v[118:121], v[34:49]
	ds_read_b128 v[186:189], v229 offset:13408
	v_exp_f32_e32 v222, v90
	v_exp_f32_e32 v223, v91
	v_add_f32_e32 v164, v222, v164
	v_cvt_pk_bf16_f32 v210, v222, v223
	v_add_f32_e32 v164, v223, v164
	s_waitcnt lgkmcnt(3)
	v_mfma_f32_32x32x16_bf16 v[50:65], v[194:197], v[118:121], v[50:65]
	ds_read_b128 v[190:193], v229 offset:20064
	v_exp_f32_e32 v224, v92
	v_exp_f32_e32 v225, v93
	v_add_f32_e32 v164, v224, v164
	v_cvt_pk_bf16_f32 v211, v224, v225
	v_add_f32_e32 v164, v225, v164
	s_waitcnt lgkmcnt(3)
	v_mfma_f32_32x32x16_bf16 v[34:49], v[198:201], v[122:125], v[34:49]
	ds_read_b128 v[194:197], v229 offset:13440
	v_exp_f32_e32 v222, v94
	v_exp_f32_e32 v223, v95
	v_add_f32_e32 v164, v222, v164
	v_cvt_pk_bf16_f32 v212, v222, v223
	v_add_f32_e32 v164, v223, v164
	s_waitcnt lgkmcnt(3)
	v_mfma_f32_32x32x16_bf16 v[50:65], v[182:185], v[122:125], v[50:65]
	ds_read_b128 v[198:201], v229 offset:20096
	v_exp_f32_e32 v224, v96
	v_exp_f32_e32 v225, v97
	v_add_f32_e32 v164, v224, v164
	v_cvt_pk_bf16_f32 v213, v224, v225
	v_add_f32_e32 v164, v225, v164
	s_waitcnt lgkmcnt(3)
	v_mfma_f32_32x32x16_bf16 v[34:49], v[186:189], v[126:129], v[34:49]
	ds_read_b128 v[182:185], v229 offset:13472
	v_exp_f32_e32 v222, v98
	v_exp_f32_e32 v223, v99
	v_add_f32_e32 v164, v222, v164
	v_cvt_pk_bf16_f32 v214, v222, v223
	v_add_f32_e32 v164, v223, v164
	s_waitcnt lgkmcnt(3)
	v_mfma_f32_32x32x16_bf16 v[50:65], v[190:193], v[126:129], v[50:65]
	ds_read_b128 v[186:189], v229 offset:20128
	v_exp_f32_e32 v224, v100
	v_exp_f32_e32 v225, v101
	v_add_f32_e32 v164, v224, v164
	v_cvt_pk_bf16_f32 v215, v224, v225
	v_add_f32_e32 v164, v225, v164
	s_mov_b32 s13, s20
	s_mov_b32 s20, s19
	s_add_i32 s19, s19, 1
	s_cmp_eq_u32 s19, s9
	s_cselect_b32 s19, 0, s19
	s_waitcnt lgkmcnt(3)
	v_mfma_f32_32x32x16_bf16 v[34:49], v[194:197], v[130:133], v[34:49]
	ds_read_b128 v[190:193], v181 offset:49152
	v_exp_f32_e32 v222, v102
	v_exp_f32_e32 v223, v103
	v_add_f32_e32 v164, v222, v164
	v_cvt_pk_bf16_f32 v216, v222, v223
	v_add_f32_e32 v164, v223, v164
	s_waitcnt vmcnt(2)
	ds_write_b128 v172, v[150:153] offset:22528
	v_lshl_add_u32 v222, s19, 17, v178
	global_load_dwordx4 v[150:153], v222, s[52:53]
	s_waitcnt lgkmcnt(4)
	v_mfma_f32_32x32x16_bf16 v[50:65], v[198:201], v[130:133], v[50:65]
	ds_read_b128 v[194:197], v181 offset:53760
	v_exp_f32_e32 v224, v104
	v_exp_f32_e32 v225, v105
	v_add_f32_e32 v164, v224, v164
	v_cvt_pk_bf16_f32 v217, v224, v225
	v_add_f32_e32 v164, v225, v164
	s_and_b64 vcc, exec, s[2:3]
	s_cbranch_vccz .Lmla_p7_nope
	ds_write_b128 v176, v[160:163] offset:22656
	v_lshl_add_u32 v222, s19, 12, v179
	global_load_dwordx4 v[160:163], v222, s[62:63]
.Lmla_p7_nope:
	s_waitcnt lgkmcnt(4)
	v_mfma_f32_32x32x16_bf16 v[34:49], v[182:185], v[134:137], v[34:49]
	ds_read_b128 v[198:201], v181 offset:49184
	v_exp_f32_e32 v222, v106
	v_exp_f32_e32 v223, v107
	v_add_f32_e32 v164, v222, v164
	v_cvt_pk_bf16_f32 v218, v222, v223
	v_add_f32_e32 v164, v223, v164
	ds_write_b128 v173, v[202:205] offset:35840
	v_lshl_add_u32 v222, s13, 7, v168
	global_load_dwordx4 v[202:205], v222, s[56:57]
	s_waitcnt lgkmcnt(5)
	v_mfma_f32_32x32x16_bf16 v[50:65], v[186:189], v[134:137], v[50:65]
	ds_read_b128 v[182:185], v181 offset:53792
	v_exp_f32_e32 v224, v108
	v_exp_f32_e32 v225, v109
	v_add_f32_e32 v164, v224, v164
	v_cvt_pk_bf16_f32 v219, v224, v225
	v_add_f32_e32 v164, v225, v164
	s_waitcnt lgkmcnt(5)
	v_mfma_f32_32x32x16_bf16 v[2:17], v[190:193], v[206:209], v[2:17]
	ds_read_b128 v[186:189], v181 offset:49216
	v_exp_f32_e32 v222, v110
	v_exp_f32_e32 v223, v111
	v_add_f32_e32 v164, v222, v164
	v_cvt_pk_bf16_f32 v220, v222, v223
	v_add_f32_e32 v164, v223, v164
	s_waitcnt lgkmcnt(4)
	v_mfma_f32_32x32x16_bf16 v[18:33], v[194:197], v[206:209], v[18:33]
	ds_read_b128 v[190:193], v181 offset:53824
	v_exp_f32_e32 v224, v112
	v_exp_f32_e32 v225, v113
	v_add_f32_e32 v164, v224, v164
	v_cvt_pk_bf16_f32 v221, v224, v225
	v_add_f32_e32 v164, v225, v164
	s_waitcnt lgkmcnt(4)
	v_mfma_f32_32x32x16_bf16 v[2:17], v[198:201], v[210:213], v[2:17]
	ds_read_b128 v[194:197], v181 offset:49248
	v_max3_f32 v224, v34, v35, v36
	v_max3_f32 v225, v50, v51, v52
	v_max3_f32 v224, v224, v37, v38
	v_max3_f32 v225, v225, v53, v54
	s_waitcnt lgkmcnt(3)
	v_mfma_f32_32x32x16_bf16 v[18:33], v[182:185], v[210:213], v[18:33]
	ds_read_b128 v[198:201], v181 offset:53856
	ds_read_b128 v[182:185], v229 offset:26624
	v_max3_f32 v224, v224, v39, v40
	v_max3_f32 v225, v225, v55, v56
	v_max3_f32 v224, v224, v41, v42
	v_max3_f32 v225, v225, v57, v58
	s_waitcnt lgkmcnt(4)
	v_mfma_f32_32x32x16_bf16 v[2:17], v[186:189], v[214:217], v[2:17]
	ds_read_b128 v[186:189], v229 offset:33280
	v_max3_f32 v224, v224, v43, v44
	v_max3_f32 v225, v225, v59, v60
	v_max3_f32 v224, v224, v45, v46
	v_max3_f32 v225, v225, v61, v62
	s_waitcnt lgkmcnt(4)
	v_mfma_f32_32x32x16_bf16 v[18:33], v[190:193], v[214:217], v[18:33]
	ds_read_b128 v[190:193], v229 offset:26656
	v_max3_f32 v224, v224, v47, v48
	v_max3_f32 v225, v225, v63, v64
	v_max3_f32 v224, v224, v49, v65
	v_max_f32_e32 v224, v224, v225
	s_waitcnt lgkmcnt(4)
	v_mfma_f32_32x32x16_bf16 v[2:17], v[194:197], v[218:221], v[2:17]
	ds_read_b128 v[194:197], v229 offset:33312
	v_mov_b32_e32 v225, v224
	v_add_f32_e32 v1, v1, v164
	s_add_i32 s11, s11, 1
	v_permlane32_swap_b32_e32 v224, v225
	s_cmp_eq_u32 s9, s11
	v_max_f32_e32 v167, v224, v225
	v_cmp_lt_f32_e32 vcc, s66, v167
	s_waitcnt lgkmcnt(4)
	v_mfma_f32_32x32x16_bf16 v[18:33], v[198:201], v[218:221], v[18:33]
	s_waitcnt lgkmcnt(9)
	s_barrier

; template <int VAR>
; __device__ __forceinline__ void attn_phase(LAS unsigned char* lds, const AttnP P, int vcu, int G, int wave_s) {
;     ...
;                 if (ND0 == 6) {
;                     KR1(0); KR1(1); KR1(2); KR1(3); SB();
;                     QK1(0, negm); EX2(pc0, 0, w0.x); KR1(4); SB();
;                     QK1(1, negm); EX2(pc0, 2, w0.y); KR1(5); SB();
;                     QK1(2, pn0); EX2(pc0, 4, w0.z); KR1(6); SB();
;                     QK1(3, pn1); EX2(pc0, 6, w0.w); KR1(7); SB();
;                     QK1(4, pn0); EX2(pc0, 8, w1.x); KR1(8); SB();
;                     QK1(5, pn1); EX2(pc0, 10, w1.y); KR1(9); SB();
;                     QK1(6, pn0); EX2(pc0, 12, w1.z); KR1(10); SB();
;                     QK1(7, pn1); EX2(pc0, 14, w1.w); KR1(11); SB();
;                     QK1(8, pn0); EX2(pc1, 0, w2.x); VR1(0); SB();
;                     QK1(9, pn1); EX2(pc1, 2, w2.y); VR1(1); SB();
;                     QK1(10, pn0); EX2(pc1, 4, w2.z); VR1(2); SB();
;                     QK1(11, pn1); EX2(pc1, 6, w2.w); VR1(3); SB();
;                 } else {
;                     KR1(0); KR1(1); KR1(2); KR1(3); SB();
;                     QK1(0, negm); EX2(pc0, 0, w0.x); EX2(pc0, 2, w0.y); KR1(4); SB();
;                     QK1(1, negm); EX2(pc0, 4, w0.z); EX2(pc0, 6, w0.w); KR1(5); SB();
;                     QK1(2, pn0); EX2(pc0, 8, w1.x); EX2(pc0, 10, w1.y); KR1(6); SB();
;                     QK1(3, pn1); EX2(pc0, 12, w1.z); EX2(pc0, 14, w1.w); KR1(7); SB();
;                     QK1(4, pn0); EX2(pc1, 0, w2.x); VR1(0); SB();
;                     QK1(5, pn1); EX2(pc1, 2, w2.y); VR1(1); SB();
;                     QK1(6, pn0); EX2(pc1, 4, w2.z); VR1(2); SB();
;                     QK1(7, pn1); EX2(pc1, 6, w2.w); VR1(3); SB();
;                 }
;                 PV1(0, w0); EX2(pc1, 8, w3.x); VR1(4); SB();
;                 PV1(1, w0); EX2(pc1, 10, w3.y); VR1(5); SB();
;                 PV1(2, w1); EX2(pc1, 12, w3.z); VR1(6); SB();
;                 PV1(3, w1); EX2(pc1, 14, w3.w); VR1(7); SB();
;                 lrun += sacc;
;                 PV1(4, w2); MASK_TILE(pn0, pn1, t + 1); SB();
;                 PV1(5, w2); SB();
;                 PV1(6, w3); SB();
;                 PV1(7, w3); rmn = rowmax32(pn0, pn1); if (!USE_NEGM) rmn -= mref; SB();
;     ...
;             if (hn) { STOREK(t & 1); STOREV((t + 1) & 1); }
;             __syncthreads();
.Lmla_p9_go:
	v_exp_f32_e32 v222, v82
	v_exp_f32_e32 v223, v83
	v_add_f32_e32 v164, 0, v222
	v_cvt_pk_bf16_f32 v206, v222, v223
	v_add_f32_e32 v164, v223, v164
	v_exp_f32_e32 v224, v84
	v_exp_f32_e32 v225, v85
	v_add_f32_e32 v164, v224, v164
	v_cvt_pk_bf16_f32 v207, v224, v225
	v_add_f32_e32 v164, v225, v164
	s_waitcnt lgkmcnt(4)
	v_mfma_f32_32x32x16_bf16 v[34:49], v[182:185], v[114:117], v[66:81]
	ds_read_b128 v[198:201], v174 offset:64
	v_exp_f32_e32 v222, v86
	v_exp_f32_e32 v223, v87
	v_add_f32_e32 v164, v222, v164
	v_cvt_pk_bf16_f32 v208, v222, v223
	v_add_f32_e32 v164, v223, v164
	s_waitcnt lgkmcnt(4)
	v_mfma_f32_32x32x16_bf16 v[50:65], v[186:189], v[114:117], v[66:81]
	ds_read_b128 v[182:185], v174 offset:6720
	v_exp_f32_e32 v224, v88
	v_exp_f32_e32 v225, v89
	v_add_f32_e32 v164, v224, v164
	v_cvt_pk_bf16_f32 v209, v224, v225
	v_add_f32_e32 v164, v225, v164
	s_waitcnt lgkmcnt(3)
	v_mfma_f32_32x32x16_bf16 v[34:49], v[190:193], v[118:121], v[34:49]
	ds_read_b128 v[186:189], v174 offset:96
	v_exp_f32_e32 v222, v90
	v_exp_f32_e32 v223, v91
	v_add_f32_e32 v164, v222, v164
	v_cvt_pk_bf16_f32 v210, v222, v223
	v_add_f32_e32 v164, v223, v164
	s_waitcnt lgkmcnt(3)
	v_mfma_f32_32x32x16_bf16 v[50:65], v[194:197], v[118:121], v[50:65]
	ds_read_b128 v[190:193], v174 offset:6752
	v_exp_f32_e32 v224, v92
	v_exp_f32_e32 v225, v93
	v_add_f32_e32 v164, v224, v164
	v_cvt_pk_bf16_f32 v211, v224, v225
	v_add_f32_e32 v164, v225, v164
	s_waitcnt lgkmcnt(3)
	v_mfma_f32_32x32x16_bf16 v[34:49], v[198:201], v[122:125], v[34:49]
	ds_read_b128 v[194:197], v174 offset:128
	v_exp_f32_e32 v222, v94
	v_exp_f32_e32 v223, v95
	v_add_f32_e32 v164, v222, v164
	v_cvt_pk_bf16_f32 v212, v222, v223
	v_add_f32_e32 v164, v223, v164
	s_waitcnt lgkmcnt(3)
	v_mfma_f32_32x32x16_bf16 v[50:65], v[182:185], v[122:125], v[50:65]
	ds_read_b128 v[198:201], v174 offset:6784
	v_exp_f32_e32 v224, v96
	v_exp_f32_e32 v225, v97
	v_add_f32_e32 v164, v224, v164
	v_cvt_pk_bf16_f32 v213, v224, v225
	v_add_f32_e32 v164, v225, v164
	s_waitcnt lgkmcnt(3)
	v_mfma_f32_32x32x16_bf16 v[34:49], v[186:189], v[126:129], v[34:49]
	ds_read_b128 v[182:185], v174 offset:160
	v_exp_f32_e32 v222, v98
	v_exp_f32_e32 v223, v99
	v_add_f32_e32 v164, v222, v164
	v_cvt_pk_bf16_f32 v214, v222, v223
	v_add_f32_e32 v164, v223, v164
	s_waitcnt lgkmcnt(3)
	v_mfma_f32_32x32x16_bf16 v[50:65], v[190:193], v[126:129], v[50:65]
	ds_read_b128 v[186:189], v174 offset:6816
	v_exp_f32_e32 v224, v100
	v_exp_f32_e32 v225, v101
	v_add_f32_e32 v164, v224, v164
	v_cvt_pk_bf16_f32 v215, v224, v225
	v_add_f32_e32 v164, v225, v164
	s_mov_b32 s13, s20
	s_mov_b32 s20, s19
	s_add_i32 s19, s19, 1
	s_cmp_eq_u32 s19, s9
	s_cselect_b32 s19, 0, s19
	s_waitcnt lgkmcnt(3)
	v_mfma_f32_32x32x16_bf16 v[34:49], v[194:197], v[130:133], v[34:49]
	ds_read_b128 v[190:193], v228 offset:35840
	v_exp_f32_e32 v222, v102
	v_exp_f32_e32 v223, v103
	v_add_f32_e32 v164, v222, v164
	v_cvt_pk_bf16_f32 v216, v222, v223
	v_add_f32_e32 v164, v223, v164
	s_waitcnt vmcnt(2)
	ds_write_b128 v172, v[150:153] offset:58368
	v_lshl_add_u32 v222, s19, 17, v178
	global_load_dwordx4 v[150:153], v222, s[52:53]
	s_waitcnt lgkmcnt(4)
	v_mfma_f32_32x32x16_bf16 v[50:65], v[198:201], v[130:133], v[50:65]
	ds_read_b128 v[194:197], v228 offset:40448
	v_exp_f32_e32 v224, v104
	v_exp_f32_e32 v225, v105
	v_add_f32_e32 v164, v224, v164
	v_cvt_pk_bf16_f32 v217, v224, v225
	v_add_f32_e32 v164, v225, v164
	s_and_b64 vcc, exec, s[2:3]
	s_cbranch_vccz .Lmla_p9_nope
	ds_write_b128 v176, v[160:163] offset:58496
	v_lshl_add_u32 v222, s19, 12, v179
	global_load_dwordx4 v[160:163], v222, s[62:63]
.Lmla_p9_nope:
	s_waitcnt lgkmcnt(4)
	v_mfma_f32_32x32x16_bf16 v[34:49], v[182:185], v[134:137], v[34:49]
	ds_read_b128 v[198:201], v228 offset:35872
	v_exp_f32_e32 v222, v106
	v_exp_f32_e32 v223, v107
	v_add_f32_e32 v164, v222, v164
	v_cvt_pk_bf16_f32 v218, v222, v223
	v_add_f32_e32 v164, v223, v164
	v_add_u32_e32 v222, 0xb000, v173
	ds_write_b128 v222, v[202:205] offset:49152
	v_lshl_add_u32 v222, s13, 7, v168
	global_load_dwordx4 v[202:205], v222, s[56:57]
	s_waitcnt lgkmcnt(5)
	v_mfma_f32_32x32x16_bf16 v[50:65], v[186:189], v[134:137], v[50:65]
	ds_read_b128 v[182:185], v228 offset:40480
	v_exp_f32_e32 v224, v108
	v_exp_f32_e32 v225, v109
	v_add_f32_e32 v164, v224, v164
	v_cvt_pk_bf16_f32 v219, v224, v225
	v_add_f32_e32 v164, v225, v164
	s_waitcnt lgkmcnt(5)
	v_mfma_f32_32x32x16_bf16 v[2:17], v[190:193], v[206:209], v[2:17]
	ds_read_b128 v[186:189], v228 offset:35904
	v_exp_f32_e32 v222, v110
	v_exp_f32_e32 v223, v111
	v_add_f32_e32 v164, v222, v164
	v_cvt_pk_bf16_f32 v220, v222, v223
	v_add_f32_e32 v164, v223, v164
	s_waitcnt lgkmcnt(4)
	v_mfma_f32_32x32x16_bf16 v[18:33], v[194:197], v[206:209], v[18:33]
	ds_read_b128 v[190:193], v228 offset:40512
	v_exp_f32_e32 v224, v112
	v_exp_f32_e32 v225, v113
	v_add_f32_e32 v164, v224, v164
	v_cvt_pk_bf16_f32 v221, v224, v225
	v_add_f32_e32 v164, v225, v164
	s_waitcnt lgkmcnt(4)
	v_mfma_f32_32x32x16_bf16 v[2:17], v[198:201], v[210:213], v[2:17]
	ds_read_b128 v[194:197], v228 offset:35936
	v_max3_f32 v224, v34, v35, v36
	v_max3_f32 v225, v50, v51, v52
	v_max3_f32 v224, v224, v37, v38
	v_max3_f32 v225, v225, v53, v54
	s_waitcnt lgkmcnt(3)
	v_mfma_f32_32x32x16_bf16 v[18:33], v[182:185], v[210:213], v[18:33]
	ds_read_b128 v[198:201], v228 offset:40544
	ds_read_b128 v[182:185], v174 offset:22528
	v_max3_f32 v224, v224, v39, v40
	v_max3_f32 v225, v225, v55, v56
	v_max3_f32 v224, v224, v41, v42
	v_max3_f32 v225, v225, v57, v58
	s_waitcnt lgkmcnt(4)
	v_mfma_f32_32x32x16_bf16 v[2:17], v[186:189], v[214:217], v[2:17]
	ds_read_b128 v[186:189], v174 offset:29184
	v_max3_f32 v224, v224, v43, v44
	v_max3_f32 v225, v225, v59, v60
	v_max3_f32 v224, v224, v45, v46
	v_max3_f32 v225, v225, v61, v62
	s_waitcnt lgkmcnt(4)
	v_mfma_f32_32x32x16_bf16 v[18:33], v[190:193], v[214:217], v[18:33]
	ds_read_b128 v[190:193], v174 offset:22560
	v_max3_f32 v224, v224, v47, v48
	v_max3_f32 v225, v225, v63, v64
	v_max3_f32 v224, v224, v49, v65
	v_max_f32_e32 v224, v224, v225
	s_waitcnt lgkmcnt(4)
	v_mfma_f32_32x32x16_bf16 v[2:17], v[194:197], v[218:221], v[2:17]
	ds_read_b128 v[194:197], v174 offset:29216
	v_mov_b32_e32 v225, v224
	v_add_f32_e32 v1, v1, v164
	s_add_i32 s11, s11, 1
	v_permlane32_swap_b32_e32 v224, v225
	s_cmp_eq_u32 s9, s11
	v_max_f32_e32 v167, v224, v225
	v_cmp_lt_f32_e32 vcc, s66, v167
	s_waitcnt lgkmcnt(4)
	v_mfma_f32_32x32x16_bf16 v[18:33], v[198:201], v[218:221], v[18:33]
	s_waitcnt lgkmcnt(9)
	s_barrier

; template <int VAR>
; __device__ __forceinline__ void attn_phase(LAS unsigned char* lds, const AttnP P, int vcu, int G, int wave_s) {
;     ...
;                 if (ND0 == 6) {
;                     KR1(0); KR1(1); KR1(2); KR1(3); SB();
;                     QK1(0, negm); EX2(pc0, 0, w0.x); KR1(4); SB();
;                     QK1(1, negm); EX2(pc0, 2, w0.y); KR1(5); SB();
;                     QK1(2, pn0); EX2(pc0, 4, w0.z); KR1(6); SB();
;                     QK1(3, pn1); EX2(pc0, 6, w0.w); KR1(7); SB();
;                     QK1(4, pn0); EX2(pc0, 8, w1.x); KR1(8); SB();
;                     QK1(5, pn1); EX2(pc0, 10, w1.y); KR1(9); SB();
;                     QK1(6, pn0); EX2(pc0, 12, w1.z); KR1(10); SB();
;                     QK1(7, pn1); EX2(pc0, 14, w1.w); KR1(11); SB();
;                     QK1(8, pn0); EX2(pc1, 0, w2.x); VR1(0); SB();
;                     QK1(9, pn1); EX2(pc1, 2, w2.y); VR1(1); SB();
;                     QK1(10, pn0); EX2(pc1, 4, w2.z); VR1(2); SB();
;                     QK1(11, pn1); EX2(pc1, 6, w2.w); VR1(3); SB();
;                 } else {
;                     KR1(0); KR1(1); KR1(2); KR1(3); SB();
;                     QK1(0, negm); EX2(pc0, 0, w0.x); EX2(pc0, 2, w0.y); KR1(4); SB();
;                     QK1(1, negm); EX2(pc0, 4, w0.z); EX2(pc0, 6, w0.w); KR1(5); SB();
;                     QK1(2, pn0); EX2(pc0, 8, w1.x); EX2(pc0, 10, w1.y); KR1(6); SB();
;                     QK1(3, pn1); EX2(pc0, 12, w1.z); EX2(pc0, 14, w1.w); KR1(7); SB();
;                     QK1(4, pn0); EX2(pc1, 0, w2.x); VR1(0); SB();
;                     QK1(5, pn1); EX2(pc1, 2, w2.y); VR1(1); SB();
;                     QK1(6, pn0); EX2(pc1, 4, w2.z); VR1(2); SB();
;                     QK1(7, pn1); EX2(pc1, 6, w2.w); VR1(3); SB();
;                 }
;                 PV1(0, w0); EX2(pc1, 8, w3.x); VR1(4); SB();
;                 PV1(1, w0); EX2(pc1, 10, w3.y); VR1(5); SB();
;                 PV1(2, w1); EX2(pc1, 12, w3.z); VR1(6); SB();
;                 PV1(3, w1); EX2(pc1, 14, w3.w); VR1(7); SB();
;                 lrun += sacc;
;                 PV1(4, w2); MASK_TILE(pn0, pn1, t + 1); SB();
;                 PV1(5, w2); SB();
;                 PV1(6, w3); SB();
;                 PV1(7, w3); rmn = rowmax32(pn0, pn1); if (!USE_NEGM) rmn -= mref; SB();
;     ...
;             if (hn) { STOREK(t & 1); STOREV((t + 1) & 1); }
;             __syncthreads();
.Lmla_p11_go:
	v_exp_f32_e32 v222, v82
	v_exp_f32_e32 v223, v83
	v_add_f32_e32 v164, 0, v222
	v_cvt_pk_bf16_f32 v206, v222, v223
	v_add_f32_e32 v164, v223, v164
	v_exp_f32_e32 v224, v84
	v_exp_f32_e32 v225, v85
	v_add_f32_e32 v164, v224, v164
	v_cvt_pk_bf16_f32 v207, v224, v225
	v_add_f32_e32 v164, v225, v164
	s_waitcnt lgkmcnt(4)
	v_mfma_f32_32x32x16_bf16 v[34:49], v[182:185], v[114:117], v[66:81]
	ds_read_b128 v[198:201], v174 offset:45120
	v_exp_f32_e32 v222, v86
	v_exp_f32_e32 v223, v87
	v_add_f32_e32 v164, v222, v164
	v_cvt_pk_bf16_f32 v208, v222, v223
	v_add_f32_e32 v164, v223, v164
	s_waitcnt lgkmcnt(4)
	v_mfma_f32_32x32x16_bf16 v[50:65], v[186:189], v[114:117], v[66:81]
	ds_read_b128 v[182:185], v174 offset:51776
	v_exp_f32_e32 v224, v88
	v_exp_f32_e32 v225, v89
	v_add_f32_e32 v164, v224, v164
	v_cvt_pk_bf16_f32 v209, v224, v225
	v_add_f32_e32 v164, v225, v164
	s_waitcnt lgkmcnt(3)
	v_mfma_f32_32x32x16_bf16 v[34:49], v[190:193], v[118:121], v[34:49]
	ds_read_b128 v[186:189], v174 offset:45152
	v_exp_f32_e32 v222, v90
	v_exp_f32_e32 v223, v91
	v_add_f32_e32 v164, v222, v164
	v_cvt_pk_bf16_f32 v210, v222, v223
	v_add_f32_e32 v164, v223, v164
	s_waitcnt lgkmcnt(3)
	v_mfma_f32_32x32x16_bf16 v[50:65], v[194:197], v[118:121], v[50:65]
	ds_read_b128 v[190:193], v174 offset:51808
	v_exp_f32_e32 v224, v92
	v_exp_f32_e32 v225, v93
	v_add_f32_e32 v164, v224, v164
	v_cvt_pk_bf16_f32 v211, v224, v225
	v_add_f32_e32 v164, v225, v164
	s_waitcnt lgkmcnt(3)
	v_mfma_f32_32x32x16_bf16 v[34:49], v[198:201], v[122:125], v[34:49]
	ds_read_b128 v[194:197], v174 offset:45184
	v_exp_f32_e32 v222, v94
	v_exp_f32_e32 v223, v95
	v_add_f32_e32 v164, v222, v164
	v_cvt_pk_bf16_f32 v212, v222, v223
	v_add_f32_e32 v164, v223, v164
	s_waitcnt lgkmcnt(3)
	v_mfma_f32_32x32x16_bf16 v[50:65], v[182:185], v[122:125], v[50:65]
	ds_read_b128 v[198:201], v174 offset:51840
	v_exp_f32_e32 v224, v96
	v_exp_f32_e32 v225, v97
	v_add_f32_e32 v164, v224, v164
	v_cvt_pk_bf16_f32 v213, v224, v225
	v_add_f32_e32 v164, v225, v164
	s_waitcnt lgkmcnt(3)
	v_mfma_f32_32x32x16_bf16 v[34:49], v[186:189], v[126:129], v[34:49]
	ds_read_b128 v[182:185], v174 offset:45216
	v_exp_f32_e32 v222, v98
	v_exp_f32_e32 v223, v99
	v_add_f32_e32 v164, v222, v164
	v_cvt_pk_bf16_f32 v214, v222, v223
	v_add_f32_e32 v164, v223, v164
	s_waitcnt lgkmcnt(3)
	v_mfma_f32_32x32x16_bf16 v[50:65], v[190:193], v[126:129], v[50:65]
	ds_read_b128 v[186:189], v174 offset:51872
	v_exp_f32_e32 v224, v100
	v_exp_f32_e32 v225, v101
	v_add_f32_e32 v164, v224, v164
	v_cvt_pk_bf16_f32 v215, v224, v225
	v_add_f32_e32 v164, v225, v164
	s_mov_b32 s13, s20
	s_mov_b32 s20, s19
	s_add_i32 s19, s19, 1
	s_cmp_eq_u32 s19, s9
	s_cselect_b32 s19, 0, s19
	s_waitcnt lgkmcnt(3)
	v_mfma_f32_32x32x16_bf16 v[34:49], v[194:197], v[130:133], v[34:49]
	ds_read_b128 v[190:193], v181 offset:49152
	v_exp_f32_e32 v222, v102
	v_exp_f32_e32 v223, v103
	v_add_f32_e32 v164, v222, v164
	v_cvt_pk_bf16_f32 v216, v222, v223
	v_add_f32_e32 v164, v223, v164
	s_waitcnt vmcnt(2)
	ds_write_b128 v172, v[150:153]
	v_lshl_add_u32 v222, s19, 17, v178
	global_load_dwordx4 v[150:153], v222, s[52:53]
	s_waitcnt lgkmcnt(4)
	v_mfma_f32_32x32x16_bf16 v[50:65], v[198:201], v[130:133], v[50:65]
	ds_read_b128 v[194:197], v181 offset:53760
	v_exp_f32_e32 v224, v104
	v_exp_f32_e32 v225, v105
	v_add_f32_e32 v164, v224, v164
	v_cvt_pk_bf16_f32 v217, v224, v225
	v_add_f32_e32 v164, v225, v164
	s_and_b64 vcc, exec, s[2:3]
	s_cbranch_vccz .Lmla_p11_nope
	ds_write_b128 v176, v[160:163] offset:128
	v_lshl_add_u32 v222, s19, 12, v179
	global_load_dwordx4 v[160:163], v222, s[62:63]
.Lmla_p11_nope:
	s_waitcnt lgkmcnt(4)
	v_mfma_f32_32x32x16_bf16 v[34:49], v[182:185], v[134:137], v[34:49]
	ds_read_b128 v[198:201], v181 offset:49184
	v_exp_f32_e32 v222, v106
	v_exp_f32_e32 v223, v107
	v_add_f32_e32 v164, v222, v164
	v_cvt_pk_bf16_f32 v218, v222, v223
	v_add_f32_e32 v164, v223, v164
	ds_write_b128 v173, v[202:205] offset:35840
	v_lshl_add_u32 v222, s13, 7, v168
	global_load_dwordx4 v[202:205], v222, s[56:57]
	s_waitcnt lgkmcnt(5)
	v_mfma_f32_32x32x16_bf16 v[50:65], v[186:189], v[134:137], v[50:65]
	ds_read_b128 v[182:185], v181 offset:53792
	v_exp_f32_e32 v224, v108
	v_exp_f32_e32 v225, v109
	v_add_f32_e32 v164, v224, v164
	v_cvt_pk_bf16_f32 v219, v224, v225
	v_add_f32_e32 v164, v225, v164
	s_waitcnt lgkmcnt(5)
	v_mfma_f32_32x32x16_bf16 v[2:17], v[190:193], v[206:209], v[2:17]
	ds_read_b128 v[186:189], v181 offset:49216
	v_exp_f32_e32 v222, v110
	v_exp_f32_e32 v223, v111
	v_add_f32_e32 v164, v222, v164
	v_cvt_pk_bf16_f32 v220, v222, v223
	v_add_f32_e32 v164, v223, v164
	s_waitcnt lgkmcnt(4)
	v_mfma_f32_32x32x16_bf16 v[18:33], v[194:197], v[206:209], v[18:33]
	ds_read_b128 v[190:193], v181 offset:53824
	v_exp_f32_e32 v224, v112
	v_exp_f32_e32 v225, v113
	v_add_f32_e32 v164, v224, v164
	v_cvt_pk_bf16_f32 v221, v224, v225
	v_add_f32_e32 v164, v225, v164
	s_waitcnt lgkmcnt(4)
	v_mfma_f32_32x32x16_bf16 v[2:17], v[198:201], v[210:213], v[2:17]
	ds_read_b128 v[194:197], v181 offset:49248
	v_max3_f32 v224, v34, v35, v36
	v_max3_f32 v225, v50, v51, v52
	v_max3_f32 v224, v224, v37, v38
	v_max3_f32 v225, v225, v53, v54
	s_waitcnt lgkmcnt(3)
	v_mfma_f32_32x32x16_bf16 v[18:33], v[182:185], v[210:213], v[18:33]
	ds_read_b128 v[198:201], v181 offset:53856
	ds_read_b128 v[182:185], v229 offset:13312
	v_max3_f32 v224, v224, v39, v40
	v_max3_f32 v225, v225, v55, v56
	v_max3_f32 v224, v224, v41, v42
	v_max3_f32 v225, v225, v57, v58
	s_waitcnt lgkmcnt(4)
	v_mfma_f32_32x32x16_bf16 v[2:17], v[186:189], v[214:217], v[2:17]
	ds_read_b128 v[186:189], v229 offset:19968
	v_max3_f32 v224, v224, v43, v44
	v_max3_f32 v225, v225, v59, v60
	v_max3_f32 v224, v224, v45, v46
	v_max3_f32 v225, v225, v61, v62
	s_waitcnt lgkmcnt(4)
	v_mfma_f32_32x32x16_bf16 v[18:33], v[190:193], v[214:217], v[18:33]
	ds_read_b128 v[190:193], v229 offset:13344
	v_max3_f32 v224, v224, v47, v48
	v_max3_f32 v225, v225, v63, v64
	v_max3_f32 v224, v224, v49, v65
	v_max_f32_e32 v224, v224, v225
	s_waitcnt lgkmcnt(4)
	v_mfma_f32_32x32x16_bf16 v[2:17], v[194:197], v[218:221], v[2:17]
	ds_read_b128 v[194:197], v229 offset:20000
	v_mov_b32_e32 v225, v224
	v_add_f32_e32 v1, v1, v164
	s_add_i32 s11, s11, 1
	v_permlane32_swap_b32_e32 v224, v225
	s_cmp_eq_u32 s9, s11
	v_max_f32_e32 v167, v224, v225
	v_cmp_lt_f32_e32 vcc, s66, v167
	s_waitcnt lgkmcnt(4)
	v_mfma_f32_32x32x16_bf16 v[18:33], v[198:201], v[218:221], v[18:33]
	s_waitcnt lgkmcnt(9)
	s_barrier

; template <int VAR>
; __device__ __forceinline__ void attn_phase(LAS unsigned char* lds, const AttnP P, int vcu, int G, int wave_s) {
;     ...
;                 if (ND0 == 6) {
;                     KR1(0); KR1(1); KR1(2); KR1(3); SB();
;                     QK1(0, negm); EX2(pc0, 0, w0.x); KR1(4); SB();
;                     QK1(1, negm); EX2(pc0, 2, w0.y); KR1(5); SB();
;                     QK1(2, pn0); EX2(pc0, 4, w0.z); KR1(6); SB();
;                     QK1(3, pn1); EX2(pc0, 6, w0.w); KR1(7); SB();
;                     QK1(4, pn0); EX2(pc0, 8, w1.x); KR1(8); SB();
;                     QK1(5, pn1); EX2(pc0, 10, w1.y); KR1(9); SB();
;                     QK1(6, pn0); EX2(pc0, 12, w1.z); KR1(10); SB();
;                     QK1(7, pn1); EX2(pc0, 14, w1.w); KR1(11); SB();
;                     QK1(8, pn0); EX2(pc1, 0, w2.x); VR1(0); SB();
;                     QK1(9, pn1); EX2(pc1, 2, w2.y); VR1(1); SB();
;                     QK1(10, pn0); EX2(pc1, 4, w2.z); VR1(2); SB();
;                     QK1(11, pn1); EX2(pc1, 6, w2.w); VR1(3); SB();
;                 } else {
;                     KR1(0); KR1(1); KR1(2); KR1(3); SB();
;                     QK1(0, negm); EX2(pc0, 0, w0.x); EX2(pc0, 2, w0.y); KR1(4); SB();
;                     QK1(1, negm); EX2(pc0, 4, w0.z); EX2(pc0, 6, w0.w); KR1(5); SB();
;                     QK1(2, pn0); EX2(pc0, 8, w1.x); EX2(pc0, 10, w1.y); KR1(6); SB();
;                     QK1(3, pn1); EX2(pc0, 12, w1.z); EX2(pc0, 14, w1.w); KR1(7); SB();
;                     QK1(4, pn0); EX2(pc1, 0, w2.x); VR1(0); SB();
;                     QK1(5, pn1); EX2(pc1, 2, w2.y); VR1(1); SB();
;                     QK1(6, pn0); EX2(pc1, 4, w2.z); VR1(2); SB();
;                     QK1(7, pn1); EX2(pc1, 6, w2.w); VR1(3); SB();
;                 }
;                 PV1(0, w0); EX2(pc1, 8, w3.x); VR1(4); SB();
;                 PV1(1, w0); EX2(pc1, 10, w3.y); VR1(5); SB();
;                 PV1(2, w1); EX2(pc1, 12, w3.z); VR1(6); SB();
;                 PV1(3, w1); EX2(pc1, 14, w3.w); VR1(7); SB();
;                 lrun += sacc;
;                 PV1(4, w2); MASK_TILE(pn0, pn1, t + 1); SB();
;                 PV1(5, w2); SB();
;                 PV1(6, w3); SB();
;                 PV1(7, w3); rmn = rowmax32(pn0, pn1); if (!USE_NEGM) rmn -= mref; SB();
;     ...
;             if (hn) { STOREK(t & 1); STOREV((t + 1) & 1); }
;             __syncthreads();
.Lmla_p13_go:
	v_exp_f32_e32 v222, v82
	v_exp_f32_e32 v223, v83
	v_add_f32_e32 v164, 0, v222
	v_cvt_pk_bf16_f32 v206, v222, v223
	v_add_f32_e32 v164, v223, v164
	v_exp_f32_e32 v224, v84
	v_exp_f32_e32 v225, v85
	v_add_f32_e32 v164, v224, v164
	v_cvt_pk_bf16_f32 v207, v224, v225
	v_add_f32_e32 v164, v225, v164
	s_waitcnt lgkmcnt(4)
	v_mfma_f32_32x32x16_bf16 v[34:49], v[182:185], v[114:117], v[66:81]
	ds_read_b128 v[198:201], v229 offset:26688
	v_exp_f32_e32 v222, v86
	v_exp_f32_e32 v223, v87
	v_add_f32_e32 v164, v222, v164
	v_cvt_pk_bf16_f32 v208, v222, v223
	v_add_f32_e32 v164, v223, v164
	s_waitcnt lgkmcnt(4)
	v_mfma_f32_32x32x16_bf16 v[50:65], v[186:189], v[114:117], v[66:81]
	ds_read_b128 v[182:185], v229 offset:33344
	v_exp_f32_e32 v224, v88
	v_exp_f32_e32 v225, v89
	v_add_f32_e32 v164, v224, v164
	v_cvt_pk_bf16_f32 v209, v224, v225
	v_add_f32_e32 v164, v225, v164
	s_waitcnt lgkmcnt(3)
	v_mfma_f32_32x32x16_bf16 v[34:49], v[190:193], v[118:121], v[34:49]
	ds_read_b128 v[186:189], v229 offset:26720
	v_exp_f32_e32 v222, v90
	v_exp_f32_e32 v223, v91
	v_add_f32_e32 v164, v222, v164
	v_cvt_pk_bf16_f32 v210, v222, v223
	v_add_f32_e32 v164, v223, v164
	s_waitcnt lgkmcnt(3)
	v_mfma_f32_32x32x16_bf16 v[50:65], v[194:197], v[118:121], v[50:65]
	ds_read_b128 v[190:193], v229 offset:33376
	v_exp_f32_e32 v224, v92
	v_exp_f32_e32 v225, v93
	v_add_f32_e32 v164, v224, v164
	v_cvt_pk_bf16_f32 v211, v224, v225
	v_add_f32_e32 v164, v225, v164
	s_waitcnt lgkmcnt(3)
	v_mfma_f32_32x32x16_bf16 v[34:49], v[198:201], v[122:125], v[34:49]
	ds_read_b128 v[194:197], v229 offset:26752
	v_exp_f32_e32 v222, v94
	v_exp_f32_e32 v223, v95
	v_add_f32_e32 v164, v222, v164
	v_cvt_pk_bf16_f32 v212, v222, v223
	v_add_f32_e32 v164, v223, v164
	s_waitcnt lgkmcnt(3)
	v_mfma_f32_32x32x16_bf16 v[50:65], v[182:185], v[122:125], v[50:65]
	ds_read_b128 v[198:201], v229 offset:33408
	v_exp_f32_e32 v224, v96
	v_exp_f32_e32 v225, v97
	v_add_f32_e32 v164, v224, v164
	v_cvt_pk_bf16_f32 v213, v224, v225
	v_add_f32_e32 v164, v225, v164
	s_waitcnt lgkmcnt(3)
	v_mfma_f32_32x32x16_bf16 v[34:49], v[186:189], v[126:129], v[34:49]
	ds_read_b128 v[182:185], v229 offset:26784
	v_exp_f32_e32 v222, v98
	v_exp_f32_e32 v223, v99
	v_add_f32_e32 v164, v222, v164
	v_cvt_pk_bf16_f32 v214, v222, v223
	v_add_f32_e32 v164, v223, v164
	s_waitcnt lgkmcnt(3)
	v_mfma_f32_32x32x16_bf16 v[50:65], v[190:193], v[126:129], v[50:65]
	ds_read_b128 v[186:189], v229 offset:33440
	v_exp_f32_e32 v224, v100
	v_exp_f32_e32 v225, v101
	v_add_f32_e32 v164, v224, v164
	v_cvt_pk_bf16_f32 v215, v224, v225
	v_add_f32_e32 v164, v225, v164
	s_mov_b32 s13, s20
	s_mov_b32 s20, s19
	s_add_i32 s19, s19, 1
	s_cmp_eq_u32 s19, s9
	s_cselect_b32 s19, 0, s19
	s_waitcnt lgkmcnt(3)
	v_mfma_f32_32x32x16_bf16 v[34:49], v[194:197], v[130:133], v[34:49]
	ds_read_b128 v[190:193], v228 offset:35840
	v_exp_f32_e32 v222, v102
	v_exp_f32_e32 v223, v103
	v_add_f32_e32 v164, v222, v164
	v_cvt_pk_bf16_f32 v216, v222, v223
	v_add_f32_e32 v164, v223, v164
	s_waitcnt vmcnt(2)
	ds_write_b128 v172, v[150:153] offset:45056
	v_lshl_add_u32 v222, s19, 17, v178
	global_load_dwordx4 v[150:153], v222, s[52:53]
	s_waitcnt lgkmcnt(4)
	v_mfma_f32_32x32x16_bf16 v[50:65], v[198:201], v[130:133], v[50:65]
	ds_read_b128 v[194:197], v228 offset:40448
	v_exp_f32_e32 v224, v104
	v_exp_f32_e32 v225, v105
	v_add_f32_e32 v164, v224, v164
	v_cvt_pk_bf16_f32 v217, v224, v225
	v_add_f32_e32 v164, v225, v164
	s_and_b64 vcc, exec, s[2:3]
	s_cbranch_vccz .Lmla_p13_nope
	ds_write_b128 v176, v[160:163] offset:45184
	v_lshl_add_u32 v222, s19, 12, v179
	global_load_dwordx4 v[160:163], v222, s[62:63]
.Lmla_p13_nope:
	s_waitcnt lgkmcnt(4)
	v_mfma_f32_32x32x16_bf16 v[34:49], v[182:185], v[134:137], v[34:49]
	ds_read_b128 v[198:201], v228 offset:35872
	v_exp_f32_e32 v222, v106
	v_exp_f32_e32 v223, v107
	v_add_f32_e32 v164, v222, v164
	v_cvt_pk_bf16_f32 v218, v222, v223
	v_add_f32_e32 v164, v223, v164
	v_add_u32_e32 v222, 0xb000, v173
	ds_write_b128 v222, v[202:205] offset:49152
	v_lshl_add_u32 v222, s13, 7, v168
	global_load_dwordx4 v[202:205], v222, s[56:57]
	s_waitcnt lgkmcnt(5)
	v_mfma_f32_32x32x16_bf16 v[50:65], v[186:189], v[134:137], v[50:65]
	ds_read_b128 v[182:185], v228 offset:40480
	v_exp_f32_e32 v224, v108
	v_exp_f32_e32 v225, v109
	v_add_f32_e32 v164, v224, v164
	v_cvt_pk_bf16_f32 v219, v224, v225
	v_add_f32_e32 v164, v225, v164
	s_waitcnt lgkmcnt(5)
	v_mfma_f32_32x32x16_bf16 v[2:17], v[190:193], v[206:209], v[2:17]
	ds_read_b128 v[186:189], v228 offset:35904
	v_exp_f32_e32 v222, v110
	v_exp_f32_e32 v223, v111
	v_add_f32_e32 v164, v222, v164
	v_cvt_pk_bf16_f32 v220, v222, v223
	v_add_f32_e32 v164, v223, v164
	s_waitcnt lgkmcnt(4)
	v_mfma_f32_32x32x16_bf16 v[18:33], v[194:197], v[206:209], v[18:33]
	ds_read_b128 v[190:193], v228 offset:40512
	v_exp_f32_e32 v224, v112
	v_exp_f32_e32 v225, v113
	v_add_f32_e32 v164, v224, v164
	v_cvt_pk_bf16_f32 v221, v224, v225
	v_add_f32_e32 v164, v225, v164
	s_waitcnt lgkmcnt(4)
	v_mfma_f32_32x32x16_bf16 v[2:17], v[198:201], v[210:213], v[2:17]
	ds_read_b128 v[194:197], v228 offset:35936
	v_max3_f32 v224, v34, v35, v36
	v_max3_f32 v225, v50, v51, v52
	v_max3_f32 v224, v224, v37, v38
	v_max3_f32 v225, v225, v53, v54
	s_waitcnt lgkmcnt(3)
	v_mfma_f32_32x32x16_bf16 v[18:33], v[182:185], v[210:213], v[18:33]
	ds_read_b128 v[198:201], v228 offset:40544
	ds_read_b128 v[182:185], v174
	v_max3_f32 v224, v224, v39, v40
	v_max3_f32 v225, v225, v55, v56
	v_max3_f32 v224, v224, v41, v42
	v_max3_f32 v225, v225, v57, v58
	s_waitcnt lgkmcnt(4)
	v_mfma_f32_32x32x16_bf16 v[2:17], v[186:189], v[214:217], v[2:17]
	ds_read_b128 v[186:189], v174 offset:6656
	v_max3_f32 v224, v224, v43, v44
	v_max3_f32 v225, v225, v59, v60
	v_max3_f32 v224, v224, v45, v46
	v_max3_f32 v225, v225, v61, v62
	s_waitcnt lgkmcnt(4)
	v_mfma_f32_32x32x16_bf16 v[18:33], v[190:193], v[214:217], v[18:33]
	ds_read_b128 v[190:193], v174 offset:32
	v_max3_f32 v224, v224, v47, v48
	v_max3_f32 v225, v225, v63, v64
	v_max3_f32 v224, v224, v49, v65
	v_max_f32_e32 v224, v224, v225
	s_waitcnt lgkmcnt(4)
	v_mfma_f32_32x32x16_bf16 v[2:17], v[194:197], v[218:221], v[2:17]
	ds_read_b128 v[194:197], v174 offset:6688
	v_mov_b32_e32 v225, v224
	v_add_f32_e32 v1, v1, v164
	s_add_i32 s11, s11, 1
	v_permlane32_swap_b32_e32 v224, v225
	s_cmp_eq_u32 s9, s11
	v_max_f32_e32 v167, v224, v225
	v_cmp_lt_f32_e32 vcc, s66, v167
	s_waitcnt lgkmcnt(4)
	v_mfma_f32_32x32x16_bf16 v[18:33], v[198:201], v[218:221], v[18:33]
	s_waitcnt lgkmcnt(9)
	s_barrier

; template <int VAR>
; __device__ __forceinline__ void attn_phase(LAS unsigned char* lds, const AttnP P, int vcu, int G, int wave_s) {
;     ...
;                 if (ND0 == 6) {
;                     KR1(0); KR1(1); KR1(2); KR1(3); SB();
;                     QK1(0, negm); EX2(pc0, 0, w0.x); KR1(4); SB();
;                     QK1(1, negm); EX2(pc0, 2, w0.y); KR1(5); SB();
;                     QK1(2, pn0); EX2(pc0, 4, w0.z); KR1(6); SB();
;                     QK1(3, pn1); EX2(pc0, 6, w0.w); KR1(7); SB();
;                     QK1(4, pn0); EX2(pc0, 8, w1.x); KR1(8); SB();
;                     QK1(5, pn1); EX2(pc0, 10, w1.y); KR1(9); SB();
;                     QK1(6, pn0); EX2(pc0, 12, w1.z); KR1(10); SB();
;                     QK1(7, pn1); EX2(pc0, 14, w1.w); KR1(11); SB();
;                     QK1(8, pn0); EX2(pc1, 0, w2.x); VR1(0); SB();
;                     QK1(9, pn1); EX2(pc1, 2, w2.y); VR1(1); SB();
;                     QK1(10, pn0); EX2(pc1, 4, w2.z); VR1(2); SB();
;                     QK1(11, pn1); EX2(pc1, 6, w2.w); VR1(3); SB();
;                 } else {
;                     KR1(0); KR1(1); KR1(2); KR1(3); SB();
;                     QK1(0, negm); EX2(pc0, 0, w0.x); EX2(pc0, 2, w0.y); KR1(4); SB();
;                     QK1(1, negm); EX2(pc0, 4, w0.z); EX2(pc0, 6, w0.w); KR1(5); SB();
;                     QK1(2, pn0); EX2(pc0, 8, w1.x); EX2(pc0, 10, w1.y); KR1(6); SB();
;                     QK1(3, pn1); EX2(pc0, 12, w1.z); EX2(pc0, 14, w1.w); KR1(7); SB();
;                     QK1(4, pn0); EX2(pc1, 0, w2.x); VR1(0); SB();
;                     QK1(5, pn1); EX2(pc1, 2, w2.y); VR1(1); SB();
;                     QK1(6, pn0); EX2(pc1, 4, w2.z); VR1(2); SB();
;                     QK1(7, pn1); EX2(pc1, 6, w2.w); VR1(3); SB();
;                 }
;                 PV1(0, w0); EX2(pc1, 8, w3.x); VR1(4); SB();
;                 PV1(1, w0); EX2(pc1, 10, w3.y); VR1(5); SB();
;                 PV1(2, w1); EX2(pc1, 12, w3.z); VR1(6); SB();
;                 PV1(3, w1); EX2(pc1, 14, w3.w); VR1(7); SB();
;                 lrun += sacc;
;                 PV1(4, w2); MASK_TILE(pn0, pn1, t + 1); SB();
;                 PV1(5, w2); SB();
;                 PV1(6, w3); SB();
;                 PV1(7, w3); rmn = rowmax32(pn0, pn1); if (!USE_NEGM) rmn -= mref; SB();
;     ...
;             if (hn) { STOREK(t & 1); STOREV((t + 1) & 1); }
;             __syncthreads();
.Lmla_p15_go:
	v_exp_f32_e32 v222, v82
	v_exp_f32_e32 v223, v83
	v_add_f32_e32 v164, 0, v222
	v_cvt_pk_bf16_f32 v206, v222, v223
	v_add_f32_e32 v164, v223, v164
	v_exp_f32_e32 v224, v84
	v_exp_f32_e32 v225, v85
	v_add_f32_e32 v164, v224, v164
	v_cvt_pk_bf16_f32 v207, v224, v225
	v_add_f32_e32 v164, v225, v164
	s_waitcnt lgkmcnt(4)
	v_mfma_f32_32x32x16_bf16 v[34:49], v[182:185], v[114:117], v[66:81]
	ds_read_b128 v[198:201], v174 offset:22592
	v_exp_f32_e32 v222, v86
	v_exp_f32_e32 v223, v87
	v_add_f32_e32 v164, v222, v164
	v_cvt_pk_bf16_f32 v208, v222, v223
	v_add_f32_e32 v164, v223, v164
	s_waitcnt lgkmcnt(4)
	v_mfma_f32_32x32x16_bf16 v[50:65], v[186:189], v[114:117], v[66:81]
	ds_read_b128 v[182:185], v174 offset:29248
	v_exp_f32_e32 v224, v88
	v_exp_f32_e32 v225, v89
	v_add_f32_e32 v164, v224, v164
	v_cvt_pk_bf16_f32 v209, v224, v225
	v_add_f32_e32 v164, v225, v164
	s_waitcnt lgkmcnt(3)
	v_mfma_f32_32x32x16_bf16 v[34:49], v[190:193], v[118:121], v[34:49]
	ds_read_b128 v[186:189], v174 offset:22624
	v_exp_f32_e32 v222, v90
	v_exp_f32_e32 v223, v91
	v_add_f32_e32 v164, v222, v164
	v_cvt_pk_bf16_f32 v210, v222, v223
	v_add_f32_e32 v164, v223, v164
	s_waitcnt lgkmcnt(3)
	v_mfma_f32_32x32x16_bf16 v[50:65], v[194:197], v[118:121], v[50:65]
	ds_read_b128 v[190:193], v174 offset:29280
	v_exp_f32_e32 v224, v92
	v_exp_f32_e32 v225, v93
	v_add_f32_e32 v164, v224, v164
	v_cvt_pk_bf16_f32 v211, v224, v225
	v_add_f32_e32 v164, v225, v164
	s_waitcnt lgkmcnt(3)
	v_mfma_f32_32x32x16_bf16 v[34:49], v[198:201], v[122:125], v[34:49]
	ds_read_b128 v[194:197], v174 offset:22656
	v_exp_f32_e32 v222, v94
	v_exp_f32_e32 v223, v95
	v_add_f32_e32 v164, v222, v164
	v_cvt_pk_bf16_f32 v212, v222, v223
	v_add_f32_e32 v164, v223, v164
	s_waitcnt lgkmcnt(3)
	v_mfma_f32_32x32x16_bf16 v[50:65], v[182:185], v[122:125], v[50:65]
	ds_read_b128 v[198:201], v174 offset:29312
	v_exp_f32_e32 v224, v96
	v_exp_f32_e32 v225, v97
	v_add_f32_e32 v164, v224, v164
	v_cvt_pk_bf16_f32 v213, v224, v225
	v_add_f32_e32 v164, v225, v164
	s_waitcnt lgkmcnt(3)
	v_mfma_f32_32x32x16_bf16 v[34:49], v[186:189], v[126:129], v[34:49]
	ds_read_b128 v[182:185], v174 offset:22688
	v_exp_f32_e32 v222, v98
	v_exp_f32_e32 v223, v99
	v_add_f32_e32 v164, v222, v164
	v_cvt_pk_bf16_f32 v214, v222, v223
	v_add_f32_e32 v164, v223, v164
	s_waitcnt lgkmcnt(3)
	v_mfma_f32_32x32x16_bf16 v[50:65], v[190:193], v[126:129], v[50:65]
	ds_read_b128 v[186:189], v174 offset:29344
	v_exp_f32_e32 v224, v100
	v_exp_f32_e32 v225, v101
	v_add_f32_e32 v164, v224, v164
	v_cvt_pk_bf16_f32 v215, v224, v225
	v_add_f32_e32 v164, v225, v164
	s_mov_b32 s13, s20
	s_mov_b32 s20, s19
	s_add_i32 s19, s19, 1
	s_cmp_eq_u32 s19, s9
	s_cselect_b32 s19, 0, s19
	s_waitcnt lgkmcnt(3)
	v_mfma_f32_32x32x16_bf16 v[34:49], v[194:197], v[130:133], v[34:49]
	ds_read_b128 v[190:193], v181 offset:49152
	v_exp_f32_e32 v222, v102
	v_exp_f32_e32 v223, v103
	v_add_f32_e32 v164, v222, v164
	v_cvt_pk_bf16_f32 v216, v222, v223
	v_add_f32_e32 v164, v223, v164
	s_waitcnt vmcnt(2)
	v_add_u32_e32 v222, 0xb000, v172
	ds_write_b128 v222, v[150:153] offset:26624
	v_lshl_add_u32 v222, s19, 17, v178
	global_load_dwordx4 v[150:153], v222, s[52:53]
	s_waitcnt lgkmcnt(4)
	v_mfma_f32_32x32x16_bf16 v[50:65], v[198:201], v[130:133], v[50:65]
	ds_read_b128 v[194:197], v181 offset:53760
	v_exp_f32_e32 v224, v104
	v_exp_f32_e32 v225, v105
	v_add_f32_e32 v164, v224, v164
	v_cvt_pk_bf16_f32 v217, v224, v225
	v_add_f32_e32 v164, v225, v164
	s_and_b64 vcc, exec, s[2:3]
	s_cbranch_vccz .Lmla_p15_nope
	v_add_u32_e32 v222, 0xb000, v176
	ds_write_b128 v222, v[160:163] offset:26752
	v_lshl_add_u32 v222, s19, 12, v179
	global_load_dwordx4 v[160:163], v222, s[62:63]
.Lmla_p15_nope:
	s_waitcnt lgkmcnt(4)
	v_mfma_f32_32x32x16_bf16 v[34:49], v[182:185], v[134:137], v[34:49]
	ds_read_b128 v[198:201], v181 offset:49184
	v_exp_f32_e32 v222, v106
	v_exp_f32_e32 v223, v107
	v_add_f32_e32 v164, v222, v164
	v_cvt_pk_bf16_f32 v218, v222, v223
	v_add_f32_e32 v164, v223, v164
	ds_write_b128 v173, v[202:205] offset:35840
	v_lshl_add_u32 v222, s13, 7, v168
	global_load_dwordx4 v[202:205], v222, s[56:57]
	s_waitcnt lgkmcnt(5)
	v_mfma_f32_32x32x16_bf16 v[50:65], v[186:189], v[134:137], v[50:65]
	ds_read_b128 v[182:185], v181 offset:53792
	v_exp_f32_e32 v224, v108
	v_exp_f32_e32 v225, v109
	v_add_f32_e32 v164, v224, v164
	v_cvt_pk_bf16_f32 v219, v224, v225
	v_add_f32_e32 v164, v225, v164
	s_waitcnt lgkmcnt(5)
	v_mfma_f32_32x32x16_bf16 v[2:17], v[190:193], v[206:209], v[2:17]
	ds_read_b128 v[186:189], v181 offset:49216
	v_exp_f32_e32 v222, v110
	v_exp_f32_e32 v223, v111
	v_add_f32_e32 v164, v222, v164
	v_cvt_pk_bf16_f32 v220, v222, v223
	v_add_f32_e32 v164, v223, v164
	s_waitcnt lgkmcnt(4)
	v_mfma_f32_32x32x16_bf16 v[18:33], v[194:197], v[206:209], v[18:33]
	ds_read_b128 v[190:193], v181 offset:53824
	v_exp_f32_e32 v224, v112
	v_exp_f32_e32 v225, v113
	v_add_f32_e32 v164, v224, v164
	v_cvt_pk_bf16_f32 v221, v224, v225
	v_add_f32_e32 v164, v225, v164
	s_waitcnt lgkmcnt(4)
	v_mfma_f32_32x32x16_bf16 v[2:17], v[198:201], v[210:213], v[2:17]
	ds_read_b128 v[194:197], v181 offset:49248
	v_max3_f32 v224, v34, v35, v36
	v_max3_f32 v225, v50, v51, v52
	v_max3_f32 v224, v224, v37, v38
	v_max3_f32 v225, v225, v53, v54
	s_waitcnt lgkmcnt(3)
	v_mfma_f32_32x32x16_bf16 v[18:33], v[182:185], v[210:213], v[18:33]
	ds_read_b128 v[198:201], v181 offset:53856
	ds_read_b128 v[182:185], v174 offset:45056
	v_max3_f32 v224, v224, v39, v40
	v_max3_f32 v225, v225, v55, v56
	v_max3_f32 v224, v224, v41, v42
	v_max3_f32 v225, v225, v57, v58
	s_waitcnt lgkmcnt(4)
	v_mfma_f32_32x32x16_bf16 v[2:17], v[186:189], v[214:217], v[2:17]
	ds_read_b128 v[186:189], v174 offset:51712
	v_max3_f32 v224, v224, v43, v44
	v_max3_f32 v225, v225, v59, v60
	v_max3_f32 v224, v224, v45, v46
	v_max3_f32 v225, v225, v61, v62
	s_waitcnt lgkmcnt(4)
	v_mfma_f32_32x32x16_bf16 v[18:33], v[190:193], v[214:217], v[18:33]
	ds_read_b128 v[190:193], v174 offset:45088
	v_max3_f32 v224, v224, v47, v48
	v_max3_f32 v225, v225, v63, v64
	v_max3_f32 v224, v224, v49, v65
	v_max_f32_e32 v224, v224, v225
	s_waitcnt lgkmcnt(4)
	v_mfma_f32_32x32x16_bf16 v[2:17], v[194:197], v[218:221], v[2:17]
	ds_read_b128 v[194:197], v174 offset:51744
	v_mov_b32_e32 v225, v224
	v_add_f32_e32 v1, v1, v164
	s_add_i32 s11, s11, 1
	v_permlane32_swap_b32_e32 v224, v225
	s_cmp_eq_u32 s9, s11
	v_max_f32_e32 v167, v224, v225
	v_cmp_lt_f32_e32 vcc, s66, v167
	s_waitcnt lgkmcnt(4)
	v_mfma_f32_32x32x16_bf16 v[18:33], v[198:201], v[218:221], v[18:33]
	s_waitcnt lgkmcnt(9)
	s_barrier

; template <int VAR>
; __device__ __forceinline__ void attn_phase(LAS unsigned char* lds, const AttnP P, int vcu, int G, int wave_s) {
;     ...
;                 if (ND0 == 6) {
;                     KR1(0); KR1(1); KR1(2); KR1(3); SB();
;                     QK1(0, negm); EX2(pc0, 0, w0.x); KR1(4); SB();
;                     QK1(1, negm); EX2(pc0, 2, w0.y); KR1(5); SB();
;                     QK1(2, pn0); EX2(pc0, 4, w0.z); KR1(6); SB();
;                     QK1(3, pn1); EX2(pc0, 6, w0.w); KR1(7); SB();
;                     QK1(4, pn0); EX2(pc0, 8, w1.x); KR1(8); SB();
;                     QK1(5, pn1); EX2(pc0, 10, w1.y); KR1(9); SB();
;                     QK1(6, pn0); EX2(pc0, 12, w1.z); KR1(10); SB();
;                     QK1(7, pn1); EX2(pc0, 14, w1.w); KR1(11); SB();
;                     QK1(8, pn0); EX2(pc1, 0, w2.x); VR1(0); SB();
;                     QK1(9, pn1); EX2(pc1, 2, w2.y); VR1(1); SB();
;                     QK1(10, pn0); EX2(pc1, 4, w2.z); VR1(2); SB();
;                     QK1(11, pn1); EX2(pc1, 6, w2.w); VR1(3); SB();
;                 } else {
;                     KR1(0); KR1(1); KR1(2); KR1(3); SB();
;                     QK1(0, negm); EX2(pc0, 0, w0.x); EX2(pc0, 2, w0.y); KR1(4); SB();
;                     QK1(1, negm); EX2(pc0, 4, w0.z); EX2(pc0, 6, w0.w); KR1(5); SB();
;                     QK1(2, pn0); EX2(pc0, 8, w1.x); EX2(pc0, 10, w1.y); KR1(6); SB();
;                     QK1(3, pn1); EX2(pc0, 12, w1.z); EX2(pc0, 14, w1.w); KR1(7); SB();
;                     QK1(4, pn0); EX2(pc1, 0, w2.x); VR1(0); SB();
;                     QK1(5, pn1); EX2(pc1, 2, w2.y); VR1(1); SB();
;                     QK1(6, pn0); EX2(pc1, 4, w2.z); VR1(2); SB();
;                     QK1(7, pn1); EX2(pc1, 6, w2.w); VR1(3); SB();
;                 }
;                 PV1(0, w0); EX2(pc1, 8, w3.x); VR1(4); SB();
;                 PV1(1, w0); EX2(pc1, 10, w3.y); VR1(5); SB();
;                 PV1(2, w1); EX2(pc1, 12, w3.z); VR1(6); SB();
;                 PV1(3, w1); EX2(pc1, 14, w3.w); VR1(7); SB();
;                 lrun += sacc;
;                 PV1(4, w2); MASK_TILE(pn0, pn1, t + 1); SB();
;                 PV1(5, w2); SB();
;                 PV1(6, w3); SB();
;                 PV1(7, w3); rmn = rowmax32(pn0, pn1); if (!USE_NEGM) rmn -= mref; SB();
;     ...
;             if (hn) { STOREK(t & 1); STOREV((t + 1) & 1); }
;             __syncthreads();
.Lmla_p17_go:
	v_exp_f32_e32 v222, v82
	v_exp_f32_e32 v223, v83
	v_add_f32_e32 v164, 0, v222
	v_cvt_pk_bf16_f32 v206, v222, v223
	v_add_f32_e32 v164, v223, v164
	v_exp_f32_e32 v224, v84
	v_exp_f32_e32 v225, v85
	v_add_f32_e32 v164, v224, v164
	v_cvt_pk_bf16_f32 v207, v224, v225
	v_add_f32_e32 v164, v225, v164
	s_waitcnt lgkmcnt(4)
	v_mfma_f32_32x32x16_bf16 v[34:49], v[182:185], v[114:117], v[66:81]
	ds_read_b128 v[198:201], v229 offset:13376
	v_exp_f32_e32 v222, v86
	v_exp_f32_e32 v223, v87
	v_add_f32_e32 v164, v222, v164
	v_cvt_pk_bf16_f32 v208, v222, v223
	v_add_f32_e32 v164, v223, v164
	s_waitcnt lgkmcnt(4)
	v_mfma_f32_32x32x16_bf16 v[50:65], v[186:189], v[114:117], v[66:81]
	ds_read_b128 v[182:185], v229 offset:20032
	v_exp_f32_e32 v224, v88
	v_exp_f32_e32 v225, v89
	v_add_f32_e32 v164, v224, v164
	v_cvt_pk_bf16_f32 v209, v224, v225
	v_add_f32_e32 v164, v225, v164
	s_waitcnt lgkmcnt(3)
	v_mfma_f32_32x32x16_bf16 v[34:49], v[190:193], v[118:121], v[34:49]
	ds_read_b128 v[186:189], v229 offset:13408
	v_exp_f32_e32 v222, v90
	v_exp_f32_e32 v223, v91
	v_add_f32_e32 v164, v222, v164
	v_cvt_pk_bf16_f32 v210, v222, v223
	v_add_f32_e32 v164, v223, v164
	s_waitcnt lgkmcnt(3)
	v_mfma_f32_32x32x16_bf16 v[50:65], v[194:197], v[118:121], v[50:65]
	ds_read_b128 v[190:193], v229 offset:20064
	v_exp_f32_e32 v224, v92
	v_exp_f32_e32 v225, v93
	v_add_f32_e32 v164, v224, v164
	v_cvt_pk_bf16_f32 v211, v224, v225
	v_add_f32_e32 v164, v225, v164
	s_waitcnt lgkmcnt(3)
	v_mfma_f32_32x32x16_bf16 v[34:49], v[198:201], v[122:125], v[34:49]
	ds_read_b128 v[194:197], v229 offset:13440
	v_exp_f32_e32 v222, v94
	v_exp_f32_e32 v223, v95
	v_add_f32_e32 v164, v222, v164
	v_cvt_pk_bf16_f32 v212, v222, v223
	v_add_f32_e32 v164, v223, v164
	s_waitcnt lgkmcnt(3)
	v_mfma_f32_32x32x16_bf16 v[50:65], v[182:185], v[122:125], v[50:65]
	ds_read_b128 v[198:201], v229 offset:20096
	v_exp_f32_e32 v224, v96
	v_exp_f32_e32 v225, v97
	v_add_f32_e32 v164, v224, v164
	v_cvt_pk_bf16_f32 v213, v224, v225
	v_add_f32_e32 v164, v225, v164
	s_waitcnt lgkmcnt(3)
	v_mfma_f32_32x32x16_bf16 v[34:49], v[186:189], v[126:129], v[34:49]
	ds_read_b128 v[182:185], v229 offset:13472
	v_exp_f32_e32 v222, v98
	v_exp_f32_e32 v223, v99
	v_add_f32_e32 v164, v222, v164
	v_cvt_pk_bf16_f32 v214, v222, v223
	v_add_f32_e32 v164, v223, v164
	s_waitcnt lgkmcnt(3)
	v_mfma_f32_32x32x16_bf16 v[50:65], v[190:193], v[126:129], v[50:65]
	ds_read_b128 v[186:189], v229 offset:20128
	v_exp_f32_e32 v224, v100
	v_exp_f32_e32 v225, v101
	v_add_f32_e32 v164, v224, v164
	v_cvt_pk_bf16_f32 v215, v224, v225
	v_add_f32_e32 v164, v225, v164
	s_mov_b32 s13, s20
	s_mov_b32 s20, s19
	s_add_i32 s19, s19, 1
	s_cmp_eq_u32 s19, s9
	s_cselect_b32 s19, 0, s19
	s_waitcnt lgkmcnt(3)
	v_mfma_f32_32x32x16_bf16 v[34:49], v[194:197], v[130:133], v[34:49]
	ds_read_b128 v[190:193], v228 offset:35840
	v_exp_f32_e32 v222, v102
	v_exp_f32_e32 v223, v103
	v_add_f32_e32 v164, v222, v164
	v_cvt_pk_bf16_f32 v216, v222, v223
	v_add_f32_e32 v164, v223, v164
	s_waitcnt vmcnt(2)
	ds_write_b128 v172, v[150:153] offset:22528
	v_lshl_add_u32 v222, s19, 17, v178
	global_load_dwordx4 v[150:153], v222, s[52:53]
	s_waitcnt lgkmcnt(4)
	v_mfma_f32_32x32x16_bf16 v[50:65], v[198:201], v[130:133], v[50:65]
	ds_read_b128 v[194:197], v228 offset:40448
	v_exp_f32_e32 v224, v104
	v_exp_f32_e32 v225, v105
	v_add_f32_e32 v164, v224, v164
	v_cvt_pk_bf16_f32 v217, v224, v225
	v_add_f32_e32 v164, v225, v164
	s_and_b64 vcc, exec, s[2:3]
	s_cbranch_vccz .Lmla_p17_nope
	ds_write_b128 v176, v[160:163] offset:22656
	v_lshl_add_u32 v222, s19, 12, v179
	global_load_dwordx4 v[160:163], v222, s[62:63]
.Lmla_p17_nope:
	s_waitcnt lgkmcnt(4)
	v_mfma_f32_32x32x16_bf16 v[34:49], v[182:185], v[134:137], v[34:49]
	ds_read_b128 v[198:201], v228 offset:35872
	v_exp_f32_e32 v222, v106
	v_exp_f32_e32 v223, v107
	v_add_f32_e32 v164, v222, v164
	v_cvt_pk_bf16_f32 v218, v222, v223
	v_add_f32_e32 v164, v223, v164
	v_add_u32_e32 v222, 0xb000, v173
	ds_write_b128 v222, v[202:205] offset:49152
	v_lshl_add_u32 v222, s13, 7, v168
	global_load_dwordx4 v[202:205], v222, s[56:57]
	s_waitcnt lgkmcnt(5)
	v_mfma_f32_32x32x16_bf16 v[50:65], v[186:189], v[134:137], v[50:65]
	ds_read_b128 v[182:185], v228 offset:40480
	v_exp_f32_e32 v224, v108
	v_exp_f32_e32 v225, v109
	v_add_f32_e32 v164, v224, v164
	v_cvt_pk_bf16_f32 v219, v224, v225
	v_add_f32_e32 v164, v225, v164
	s_waitcnt lgkmcnt(5)
	v_mfma_f32_32x32x16_bf16 v[2:17], v[190:193], v[206:209], v[2:17]
	ds_read_b128 v[186:189], v228 offset:35904
	v_exp_f32_e32 v222, v110
	v_exp_f32_e32 v223, v111
	v_add_f32_e32 v164, v222, v164
	v_cvt_pk_bf16_f32 v220, v222, v223
	v_add_f32_e32 v164, v223, v164
	s_waitcnt lgkmcnt(4)
	v_mfma_f32_32x32x16_bf16 v[18:33], v[194:197], v[206:209], v[18:33]
	ds_read_b128 v[190:193], v228 offset:40512
	v_exp_f32_e32 v224, v112
	v_exp_f32_e32 v225, v113
	v_add_f32_e32 v164, v224, v164
	v_cvt_pk_bf16_f32 v221, v224, v225
	v_add_f32_e32 v164, v225, v164
	s_waitcnt lgkmcnt(4)
	v_mfma_f32_32x32x16_bf16 v[2:17], v[198:201], v[210:213], v[2:17]
	ds_read_b128 v[194:197], v228 offset:35936
	v_max3_f32 v224, v34, v35, v36
	v_max3_f32 v225, v50, v51, v52
	v_max3_f32 v224, v224, v37, v38
	v_max3_f32 v225, v225, v53, v54
	s_waitcnt lgkmcnt(3)
	v_mfma_f32_32x32x16_bf16 v[18:33], v[182:185], v[210:213], v[18:33]
	ds_read_b128 v[198:201], v228 offset:40544
	ds_read_b128 v[182:185], v229 offset:26624
	v_max3_f32 v224, v224, v39, v40
	v_max3_f32 v225, v225, v55, v56
	v_max3_f32 v224, v224, v41, v42
	v_max3_f32 v225, v225, v57, v58
	s_waitcnt lgkmcnt(4)
	v_mfma_f32_32x32x16_bf16 v[2:17], v[186:189], v[214:217], v[2:17]
	ds_read_b128 v[186:189], v229 offset:33280
	v_max3_f32 v224, v224, v43, v44
	v_max3_f32 v225, v225, v59, v60
	v_max3_f32 v224, v224, v45, v46
	v_max3_f32 v225, v225, v61, v62
	s_waitcnt lgkmcnt(4)
	v_mfma_f32_32x32x16_bf16 v[18:33], v[190:193], v[214:217], v[18:33]
	ds_read_b128 v[190:193], v229 offset:26656
	v_max3_f32 v224, v224, v47, v48
	v_max3_f32 v225, v225, v63, v64
	v_max3_f32 v224, v224, v49, v65
	v_max_f32_e32 v224, v224, v225
	s_waitcnt lgkmcnt(4)
	v_mfma_f32_32x32x16_bf16 v[2:17], v[194:197], v[218:221], v[2:17]
	ds_read_b128 v[194:197], v229 offset:33312
	v_mov_b32_e32 v225, v224
	v_add_f32_e32 v1, v1, v164
	s_add_i32 s11, s11, 1
	v_permlane32_swap_b32_e32 v224, v225
	s_cmp_eq_u32 s9, s11
	v_max_f32_e32 v167, v224, v225
	v_cmp_lt_f32_e32 vcc, s66, v167
	s_waitcnt lgkmcnt(4)
	v_mfma_f32_32x32x16_bf16 v[18:33], v[198:201], v[218:221], v[18:33]
	s_waitcnt lgkmcnt(9)
	s_barrier

; template <int VAR>
; __device__ __forceinline__ void attn_phase(LAS unsigned char* lds, const AttnP P, int vcu, int G, int wave_s) {
;     ...
;                 if (ND0 == 6) {
;                     KR1(0); KR1(1); KR1(2); KR1(3); SB();
;                     QK1(0, negm); EX2(pc0, 0, w0.x); KR1(4); SB();
;                     QK1(1, negm); EX2(pc0, 2, w0.y); KR1(5); SB();
;                     QK1(2, pn0); EX2(pc0, 4, w0.z); KR1(6); SB();
;                     QK1(3, pn1); EX2(pc0, 6, w0.w); KR1(7); SB();
;                     QK1(4, pn0); EX2(pc0, 8, w1.x); KR1(8); SB();
;                     QK1(5, pn1); EX2(pc0, 10, w1.y); KR1(9); SB();
;                     QK1(6, pn0); EX2(pc0, 12, w1.z); KR1(10); SB();
;                     QK1(7, pn1); EX2(pc0, 14, w1.w); KR1(11); SB();
;                     QK1(8, pn0); EX2(pc1, 0, w2.x); VR1(0); SB();
;                     QK1(9, pn1); EX2(pc1, 2, w2.y); VR1(1); SB();
;                     QK1(10, pn0); EX2(pc1, 4, w2.z); VR1(2); SB();
;                     QK1(11, pn1); EX2(pc1, 6, w2.w); VR1(3); SB();
;                 } else {
;                     KR1(0); KR1(1); KR1(2); KR1(3); SB();
;                     QK1(0, negm); EX2(pc0, 0, w0.x); EX2(pc0, 2, w0.y); KR1(4); SB();
;                     QK1(1, negm); EX2(pc0, 4, w0.z); EX2(pc0, 6, w0.w); KR1(5); SB();
;                     QK1(2, pn0); EX2(pc0, 8, w1.x); EX2(pc0, 10, w1.y); KR1(6); SB();
;                     QK1(3, pn1); EX2(pc0, 12, w1.z); EX2(pc0, 14, w1.w); KR1(7); SB();
;                     QK1(4, pn0); EX2(pc1, 0, w2.x); VR1(0); SB();
;                     QK1(5, pn1); EX2(pc1, 2, w2.y); VR1(1); SB();
;                     QK1(6, pn0); EX2(pc1, 4, w2.z); VR1(2); SB();
;                     QK1(7, pn1); EX2(pc1, 6, w2.w); VR1(3); SB();
;                 }
;                 PV1(0, w0); EX2(pc1, 8, w3.x); VR1(4); SB();
;                 PV1(1, w0); EX2(pc1, 10, w3.y); VR1(5); SB();
;                 PV1(2, w1); EX2(pc1, 12, w3.z); VR1(6); SB();
;                 PV1(3, w1); EX2(pc1, 14, w3.w); VR1(7); SB();
;                 lrun += sacc;
;                 PV1(4, w2); MASK_TILE(pn0, pn1, t + 1); SB();
;                 PV1(5, w2); SB();
;                 PV1(6, w3); SB();
;                 PV1(7, w3); rmn = rowmax32(pn0, pn1); if (!USE_NEGM) rmn -= mref; SB();
;     ...
;             if (hn) { STOREK(t & 1); STOREV((t + 1) & 1); }
;             __syncthreads();
.Lmla_p19_go:
	v_exp_f32_e32 v222, v82
	v_exp_f32_e32 v223, v83
	v_add_f32_e32 v164, 0, v222
	v_cvt_pk_bf16_f32 v206, v222, v223
	v_add_f32_e32 v164, v223, v164
	v_exp_f32_e32 v224, v84
	v_exp_f32_e32 v225, v85
	v_add_f32_e32 v164, v224, v164
	v_cvt_pk_bf16_f32 v207, v224, v225
	v_add_f32_e32 v164, v225, v164
	s_waitcnt lgkmcnt(4)
	v_mfma_f32_32x32x16_bf16 v[34:49], v[182:185], v[114:117], v[66:81]
	ds_read_b128 v[198:201], v174 offset:64
	v_exp_f32_e32 v222, v86
	v_exp_f32_e32 v223, v87
	v_add_f32_e32 v164, v222, v164
	v_cvt_pk_bf16_f32 v208, v222, v223
	v_add_f32_e32 v164, v223, v164
	s_waitcnt lgkmcnt(4)
	v_mfma_f32_32x32x16_bf16 v[50:65], v[186:189], v[114:117], v[66:81]
	ds_read_b128 v[182:185], v174 offset:6720
	v_exp_f32_e32 v224, v88
	v_exp_f32_e32 v225, v89
	v_add_f32_e32 v164, v224, v164
	v_cvt_pk_bf16_f32 v209, v224, v225
	v_add_f32_e32 v164, v225, v164
	s_waitcnt lgkmcnt(3)
	v_mfma_f32_32x32x16_bf16 v[34:49], v[190:193], v[118:121], v[34:49]
	ds_read_b128 v[186:189], v174 offset:96
	v_exp_f32_e32 v222, v90
	v_exp_f32_e32 v223, v91
	v_add_f32_e32 v164, v222, v164
	v_cvt_pk_bf16_f32 v210, v222, v223
	v_add_f32_e32 v164, v223, v164
	s_waitcnt lgkmcnt(3)
	v_mfma_f32_32x32x16_bf16 v[50:65], v[194:197], v[118:121], v[50:65]
	ds_read_b128 v[190:193], v174 offset:6752
	v_exp_f32_e32 v224, v92
	v_exp_f32_e32 v225, v93
	v_add_f32_e32 v164, v224, v164
	v_cvt_pk_bf16_f32 v211, v224, v225
	v_add_f32_e32 v164, v225, v164
	s_waitcnt lgkmcnt(3)
	v_mfma_f32_32x32x16_bf16 v[34:49], v[198:201], v[122:125], v[34:49]
	ds_read_b128 v[194:197], v174 offset:128
	v_exp_f32_e32 v222, v94
	v_exp_f32_e32 v223, v95
	v_add_f32_e32 v164, v222, v164
	v_cvt_pk_bf16_f32 v212, v222, v223
	v_add_f32_e32 v164, v223, v164
	s_waitcnt lgkmcnt(3)
	v_mfma_f32_32x32x16_bf16 v[50:65], v[182:185], v[122:125], v[50:65]
	ds_read_b128 v[198:201], v174 offset:6784
	v_exp_f32_e32 v224, v96
	v_exp_f32_e32 v225, v97
	v_add_f32_e32 v164, v224, v164
	v_cvt_pk_bf16_f32 v213, v224, v225
	v_add_f32_e32 v164, v225, v164
	s_waitcnt lgkmcnt(3)
	v_mfma_f32_32x32x16_bf16 v[34:49], v[186:189], v[126:129], v[34:49]
	ds_read_b128 v[182:185], v174 offset:160
	v_exp_f32_e32 v222, v98
	v_exp_f32_e32 v223, v99
	v_add_f32_e32 v164, v222, v164
	v_cvt_pk_bf16_f32 v214, v222, v223
	v_add_f32_e32 v164, v223, v164
	s_waitcnt lgkmcnt(3)
	v_mfma_f32_32x32x16_bf16 v[50:65], v[190:193], v[126:129], v[50:65]
	ds_read_b128 v[186:189], v174 offset:6816
	v_exp_f32_e32 v224, v100
	v_exp_f32_e32 v225, v101
	v_add_f32_e32 v164, v224, v164
	v_cvt_pk_bf16_f32 v215, v224, v225
	v_add_f32_e32 v164, v225, v164
	s_mov_b32 s13, s20
	s_mov_b32 s20, s19
	s_add_i32 s19, s19, 1
	s_cmp_eq_u32 s19, s9
	s_cselect_b32 s19, 0, s19
	s_waitcnt lgkmcnt(3)
	v_mfma_f32_32x32x16_bf16 v[34:49], v[194:197], v[130:133], v[34:49]
	ds_read_b128 v[190:193], v181 offset:49152
	v_exp_f32_e32 v222, v102
	v_exp_f32_e32 v223, v103
	v_add_f32_e32 v164, v222, v164
	v_cvt_pk_bf16_f32 v216, v222, v223
	v_add_f32_e32 v164, v223, v164
	s_waitcnt vmcnt(2)
	ds_write_b128 v172, v[150:153] offset:58368
	v_lshl_add_u32 v222, s19, 17, v178
	global_load_dwordx4 v[150:153], v222, s[52:53]
	s_waitcnt lgkmcnt(4)
	v_mfma_f32_32x32x16_bf16 v[50:65], v[198:201], v[130:133], v[50:65]
	ds_read_b128 v[194:197], v181 offset:53760
	v_exp_f32_e32 v224, v104
	v_exp_f32_e32 v225, v105
	v_add_f32_e32 v164, v224, v164
	v_cvt_pk_bf16_f32 v217, v224, v225
	v_add_f32_e32 v164, v225, v164
	s_and_b64 vcc, exec, s[2:3]
	s_cbranch_vccz .Lmla_p19_nope
	ds_write_b128 v176, v[160:163] offset:58496
	v_lshl_add_u32 v222, s19, 12, v179
	global_load_dwordx4 v[160:163], v222, s[62:63]
.Lmla_p19_nope:
	s_waitcnt lgkmcnt(4)
	v_mfma_f32_32x32x16_bf16 v[34:49], v[182:185], v[134:137], v[34:49]
	ds_read_b128 v[198:201], v181 offset:49184
	v_exp_f32_e32 v222, v106
	v_exp_f32_e32 v223, v107
	v_add_f32_e32 v164, v222, v164
	v_cvt_pk_bf16_f32 v218, v222, v223
	v_add_f32_e32 v164, v223, v164
	ds_write_b128 v173, v[202:205] offset:35840
	v_lshl_add_u32 v222, s13, 7, v168
	global_load_dwordx4 v[202:205], v222, s[56:57]
	s_waitcnt lgkmcnt(5)
	v_mfma_f32_32x32x16_bf16 v[50:65], v[186:189], v[134:137], v[50:65]
	ds_read_b128 v[182:185], v181 offset:53792
	v_exp_f32_e32 v224, v108
	v_exp_f32_e32 v225, v109
	v_add_f32_e32 v164, v224, v164
	v_cvt_pk_bf16_f32 v219, v224, v225
	v_add_f32_e32 v164, v225, v164
	s_waitcnt lgkmcnt(5)
	v_mfma_f32_32x32x16_bf16 v[2:17], v[190:193], v[206:209], v[2:17]
	ds_read_b128 v[186:189], v181 offset:49216
	v_exp_f32_e32 v222, v110
	v_exp_f32_e32 v223, v111
	v_add_f32_e32 v164, v222, v164
	v_cvt_pk_bf16_f32 v220, v222, v223
	v_add_f32_e32 v164, v223, v164
	s_waitcnt lgkmcnt(4)
	v_mfma_f32_32x32x16_bf16 v[18:33], v[194:197], v[206:209], v[18:33]
	ds_read_b128 v[190:193], v181 offset:53824
	v_exp_f32_e32 v224, v112
	v_exp_f32_e32 v225, v113
	v_add_f32_e32 v164, v224, v164
	v_cvt_pk_bf16_f32 v221, v224, v225
	v_add_f32_e32 v164, v225, v164
	s_waitcnt lgkmcnt(4)
	v_mfma_f32_32x32x16_bf16 v[2:17], v[198:201], v[210:213], v[2:17]
	ds_read_b128 v[194:197], v181 offset:49248
	v_max3_f32 v224, v34, v35, v36
	v_max3_f32 v225, v50, v51, v52
	v_max3_f32 v224, v224, v37, v38
	v_max3_f32 v225, v225, v53, v54
	s_waitcnt lgkmcnt(3)
	v_mfma_f32_32x32x16_bf16 v[18:33], v[182:185], v[210:213], v[18:33]
	ds_read_b128 v[198:201], v181 offset:53856
	ds_read_b128 v[182:185], v174 offset:22528
	v_max3_f32 v224, v224, v39, v40
	v_max3_f32 v225, v225, v55, v56
	v_max3_f32 v224, v224, v41, v42
	v_max3_f32 v225, v225, v57, v58
	s_waitcnt lgkmcnt(4)
	v_mfma_f32_32x32x16_bf16 v[2:17], v[186:189], v[214:217], v[2:17]
	ds_read_b128 v[186:189], v174 offset:29184
	v_max3_f32 v224, v224, v43, v44
	v_max3_f32 v225, v225, v59, v60
	v_max3_f32 v224, v224, v45, v46
	v_max3_f32 v225, v225, v61, v62
	s_waitcnt lgkmcnt(4)
	v_mfma_f32_32x32x16_bf16 v[18:33], v[190:193], v[214:217], v[18:33]
	ds_read_b128 v[190:193], v174 offset:22560
	v_max3_f32 v224, v224, v47, v48
	v_max3_f32 v225, v225, v63, v64
	v_max3_f32 v224, v224, v49, v65
	v_max_f32_e32 v224, v224, v225
	s_waitcnt lgkmcnt(4)
	v_mfma_f32_32x32x16_bf16 v[2:17], v[194:197], v[218:221], v[2:17]
	ds_read_b128 v[194:197], v174 offset:29216
	v_mov_b32_e32 v225, v224
	v_add_f32_e32 v1, v1, v164
	s_add_i32 s11, s11, 1
	v_permlane32_swap_b32_e32 v224, v225
	s_cmp_eq_u32 s9, s11
	v_max_f32_e32 v167, v224, v225
	v_cmp_lt_f32_e32 vcc, s66, v167
	s_waitcnt lgkmcnt(4)
	v_mfma_f32_32x32x16_bf16 v[18:33], v[198:201], v[218:221], v[18:33]
	s_waitcnt lgkmcnt(9)
	s_barrier
	s_branch .Lmla_p0
